# FF2 owner epilogue (prompt tiles): pre-pass streams slot partials and x rows through a 9-quad register ring, acc updated in place; per-group code reads acc
# baseline (speedup 1.0000x reference)
.LBB0_1572:
	s_or_b64 exec, exec, s[80:81]
	s_mov_b64 s[80:81], 0
	s_branch .LBB0_1573

.Lfq_LBB0_1423:
	v_lshlrev_b32_e32 v203, 12, v204
	v_lshl_add_u32 v203, v200, 2, v203
	v_lshlrev_b32_e32 v205, 2, v194
	s_cmp_eq_u32 s30, 1
	s_cbranch_scc1 .Lfq_np1
	s_cmp_eq_u32 s30, 2
	s_cbranch_scc1 .Lfq_np2
	s_add_u32 s42, s62, 0x0
	s_addc_u32 s43, s63, 0
	global_load_dwordx4 v[160:163], v205, s[42:43]
	s_add_u32 s98, s62, 0x1000
	s_addc_u32 s99, s63, 0
	global_load_dwordx4 v[164:167], v205, s[98:99]
	s_add_u32 s42, s62, 0x400
	s_addc_u32 s43, s63, 0
	global_load_dwordx4 v[168:171], v205, s[42:43]
	s_add_u32 s98, s62, 0x1400
	s_addc_u32 s99, s63, 0
	global_load_dwordx4 v[172:175], v205, s[98:99]
	s_add_u32 s42, s62, 0x800
	s_addc_u32 s43, s63, 0
	global_load_dwordx4 v[176:179], v205, s[42:43]
	s_add_u32 s98, s62, 0x1800
	s_addc_u32 s99, s63, 0
	global_load_dwordx4 v[180:183], v205, s[98:99]
	s_add_u32 s42, s62, 0xc00
	s_addc_u32 s43, s63, 0
	global_load_dwordx4 v[206:209], v205, s[42:43]
	s_add_u32 s98, s62, 0x1c00
	s_addc_u32 s99, s63, 0
	global_load_dwordx4 v[210:213], v205, s[98:99]
	s_add_u32 s42, s62, 0x2000
	s_addc_u32 s43, s63, 0
	global_load_dwordx4 v[236:239], v205, s[42:43]
	s_waitcnt vmcnt(8)
	v_lshlrev_b32_e32 v240, 16, v160
	v_and_b32_e32 v241, 0xffff0000, v160
	v_pk_add_f32 v[124:125], v[124:125], v[240:241]
	v_lshlrev_b32_e32 v240, 16, v161
	v_and_b32_e32 v241, 0xffff0000, v161
	v_pk_add_f32 v[126:127], v[126:127], v[240:241]
	v_lshlrev_b32_e32 v240, 16, v162
	v_and_b32_e32 v241, 0xffff0000, v162
	v_pk_add_f32 v[120:121], v[120:121], v[240:241]
	v_lshlrev_b32_e32 v240, 16, v163
	v_and_b32_e32 v241, 0xffff0000, v163
	v_pk_add_f32 v[122:123], v[122:123], v[240:241]
	s_add_u32 s98, s62, 0x3000
	s_addc_u32 s99, s63, 0
	global_load_dwordx4 v[160:163], v205, s[98:99]
	s_waitcnt vmcnt(8)
	v_lshlrev_b32_e32 v240, 16, v164
	v_and_b32_e32 v241, 0xffff0000, v164
	v_pk_add_f32 v[92:93], v[92:93], v[240:241]
	v_lshlrev_b32_e32 v240, 16, v165
	v_and_b32_e32 v241, 0xffff0000, v165
	v_pk_add_f32 v[94:95], v[94:95], v[240:241]
	v_lshlrev_b32_e32 v240, 16, v166
	v_and_b32_e32 v241, 0xffff0000, v166
	v_pk_add_f32 v[88:89], v[88:89], v[240:241]
	v_lshlrev_b32_e32 v240, 16, v167
	v_and_b32_e32 v241, 0xffff0000, v167
	v_pk_add_f32 v[90:91], v[90:91], v[240:241]
	s_add_u32 s42, s62, 0x2400
	s_addc_u32 s43, s63, 0
	global_load_dwordx4 v[164:167], v205, s[42:43]
	s_waitcnt vmcnt(8)
	v_lshlrev_b32_e32 v240, 16, v168
	v_and_b32_e32 v241, 0xffff0000, v168
	v_pk_add_f32 v[116:117], v[116:117], v[240:241]
	v_lshlrev_b32_e32 v240, 16, v169
	v_and_b32_e32 v241, 0xffff0000, v169
	v_pk_add_f32 v[118:119], v[118:119], v[240:241]
	v_lshlrev_b32_e32 v240, 16, v170
	v_and_b32_e32 v241, 0xffff0000, v170
	v_pk_add_f32 v[112:113], v[112:113], v[240:241]
	v_lshlrev_b32_e32 v240, 16, v171
	v_and_b32_e32 v241, 0xffff0000, v171
	v_pk_add_f32 v[114:115], v[114:115], v[240:241]
	s_add_u32 s98, s62, 0x3400
	s_addc_u32 s99, s63, 0
	global_load_dwordx4 v[168:171], v205, s[98:99]
	s_waitcnt vmcnt(8)
	v_lshlrev_b32_e32 v240, 16, v172
	v_and_b32_e32 v241, 0xffff0000, v172
	v_pk_add_f32 v[84:85], v[84:85], v[240:241]
	v_lshlrev_b32_e32 v240, 16, v173
	v_and_b32_e32 v241, 0xffff0000, v173
	v_pk_add_f32 v[86:87], v[86:87], v[240:241]
	v_lshlrev_b32_e32 v240, 16, v174
	v_and_b32_e32 v241, 0xffff0000, v174
	v_pk_add_f32 v[80:81], v[80:81], v[240:241]
	v_lshlrev_b32_e32 v240, 16, v175
	v_and_b32_e32 v241, 0xffff0000, v175
	v_pk_add_f32 v[82:83], v[82:83], v[240:241]
	s_add_u32 s42, s62, 0x2800
	s_addc_u32 s43, s63, 0
	global_load_dwordx4 v[172:175], v205, s[42:43]
	s_waitcnt vmcnt(8)
	v_lshlrev_b32_e32 v240, 16, v176
	v_and_b32_e32 v241, 0xffff0000, v176
	v_pk_add_f32 v[108:109], v[108:109], v[240:241]
	v_lshlrev_b32_e32 v240, 16, v177
	v_and_b32_e32 v241, 0xffff0000, v177
	v_pk_add_f32 v[110:111], v[110:111], v[240:241]
	v_lshlrev_b32_e32 v240, 16, v178
	v_and_b32_e32 v241, 0xffff0000, v178
	v_pk_add_f32 v[104:105], v[104:105], v[240:241]
	v_lshlrev_b32_e32 v240, 16, v179
	v_and_b32_e32 v241, 0xffff0000, v179
	v_pk_add_f32 v[106:107], v[106:107], v[240:241]
	s_add_u32 s98, s62, 0x3800
	s_addc_u32 s99, s63, 0
	global_load_dwordx4 v[176:179], v205, s[98:99]
	s_waitcnt vmcnt(8)
	v_lshlrev_b32_e32 v240, 16, v180
	v_and_b32_e32 v241, 0xffff0000, v180
	v_pk_add_f32 v[76:77], v[76:77], v[240:241]
	v_lshlrev_b32_e32 v240, 16, v181
	v_and_b32_e32 v241, 0xffff0000, v181
	v_pk_add_f32 v[78:79], v[78:79], v[240:241]
	v_lshlrev_b32_e32 v240, 16, v182
	v_and_b32_e32 v241, 0xffff0000, v182
	v_pk_add_f32 v[72:73], v[72:73], v[240:241]
	v_lshlrev_b32_e32 v240, 16, v183
	v_and_b32_e32 v241, 0xffff0000, v183
	v_pk_add_f32 v[74:75], v[74:75], v[240:241]
	s_add_u32 s42, s62, 0x2c00
	s_addc_u32 s43, s63, 0
	global_load_dwordx4 v[180:183], v205, s[42:43]
	s_waitcnt vmcnt(8)
	v_lshlrev_b32_e32 v240, 16, v206
	v_and_b32_e32 v241, 0xffff0000, v206
	v_pk_add_f32 v[100:101], v[100:101], v[240:241]
	v_lshlrev_b32_e32 v240, 16, v207
	v_and_b32_e32 v241, 0xffff0000, v207
	v_pk_add_f32 v[102:103], v[102:103], v[240:241]
	v_lshlrev_b32_e32 v240, 16, v208
	v_and_b32_e32 v241, 0xffff0000, v208
	v_pk_add_f32 v[96:97], v[96:97], v[240:241]
	v_lshlrev_b32_e32 v240, 16, v209
	v_and_b32_e32 v241, 0xffff0000, v209
	v_pk_add_f32 v[98:99], v[98:99], v[240:241]
	s_add_u32 s98, s62, 0x3c00
	s_addc_u32 s99, s63, 0
	global_load_dwordx4 v[206:209], v205, s[98:99]
	s_waitcnt vmcnt(8)
	v_lshlrev_b32_e32 v240, 16, v210
	v_and_b32_e32 v241, 0xffff0000, v210
	v_pk_add_f32 v[68:69], v[68:69], v[240:241]
	v_lshlrev_b32_e32 v240, 16, v211
	v_and_b32_e32 v241, 0xffff0000, v211
	v_pk_add_f32 v[70:71], v[70:71], v[240:241]
	v_lshlrev_b32_e32 v240, 16, v212
	v_and_b32_e32 v241, 0xffff0000, v212
	v_pk_add_f32 v[64:65], v[64:65], v[240:241]
	v_lshlrev_b32_e32 v240, 16, v213
	v_and_b32_e32 v241, 0xffff0000, v213
	v_pk_add_f32 v[66:67], v[66:67], v[240:241]
	s_add_u32 s42, s62, 0x20000
	s_addc_u32 s43, s63, 0
	global_load_dwordx4 v[210:213], v205, s[42:43]
	s_waitcnt vmcnt(8)
	v_lshlrev_b32_e32 v240, 16, v236
	v_and_b32_e32 v241, 0xffff0000, v236
	v_pk_add_f32 v[60:61], v[60:61], v[240:241]
	v_lshlrev_b32_e32 v240, 16, v237
	v_and_b32_e32 v241, 0xffff0000, v237
	v_pk_add_f32 v[62:63], v[62:63], v[240:241]
	v_lshlrev_b32_e32 v240, 16, v238
	v_and_b32_e32 v241, 0xffff0000, v238
	v_pk_add_f32 v[56:57], v[56:57], v[240:241]
	v_lshlrev_b32_e32 v240, 16, v239
	v_and_b32_e32 v241, 0xffff0000, v239
	v_pk_add_f32 v[58:59], v[58:59], v[240:241]
	s_add_u32 s98, s62, 0x21000
	s_addc_u32 s99, s63, 0
	global_load_dwordx4 v[236:239], v205, s[98:99]
	s_waitcnt vmcnt(8)
	v_lshlrev_b32_e32 v240, 16, v160
	v_and_b32_e32 v241, 0xffff0000, v160
	v_pk_add_f32 v[28:29], v[28:29], v[240:241]
	v_lshlrev_b32_e32 v240, 16, v161
	v_and_b32_e32 v241, 0xffff0000, v161
	v_pk_add_f32 v[30:31], v[30:31], v[240:241]
	v_lshlrev_b32_e32 v240, 16, v162
	v_and_b32_e32 v241, 0xffff0000, v162
	v_pk_add_f32 v[24:25], v[24:25], v[240:241]
	v_lshlrev_b32_e32 v240, 16, v163
	v_and_b32_e32 v241, 0xffff0000, v163
	v_pk_add_f32 v[26:27], v[26:27], v[240:241]
	s_add_u32 s42, s62, 0x20400
	s_addc_u32 s43, s63, 0
	global_load_dwordx4 v[160:163], v205, s[42:43]
	s_waitcnt vmcnt(8)
	v_lshlrev_b32_e32 v240, 16, v164
	v_and_b32_e32 v241, 0xffff0000, v164
	v_pk_add_f32 v[52:53], v[52:53], v[240:241]
	v_lshlrev_b32_e32 v240, 16, v165
	v_and_b32_e32 v241, 0xffff0000, v165
	v_pk_add_f32 v[54:55], v[54:55], v[240:241]
	v_lshlrev_b32_e32 v240, 16, v166
	v_and_b32_e32 v241, 0xffff0000, v166
	v_pk_add_f32 v[48:49], v[48:49], v[240:241]
	v_lshlrev_b32_e32 v240, 16, v167
	v_and_b32_e32 v241, 0xffff0000, v167
	v_pk_add_f32 v[50:51], v[50:51], v[240:241]
	s_add_u32 s98, s62, 0x21400
	s_addc_u32 s99, s63, 0
	global_load_dwordx4 v[164:167], v205, s[98:99]
	s_waitcnt vmcnt(8)
	v_lshlrev_b32_e32 v240, 16, v168
	v_and_b32_e32 v241, 0xffff0000, v168
	v_pk_add_f32 v[20:21], v[20:21], v[240:241]
	v_lshlrev_b32_e32 v240, 16, v169
	v_and_b32_e32 v241, 0xffff0000, v169
	v_pk_add_f32 v[22:23], v[22:23], v[240:241]
	v_lshlrev_b32_e32 v240, 16, v170
	v_and_b32_e32 v241, 0xffff0000, v170
	v_pk_add_f32 v[16:17], v[16:17], v[240:241]
	v_lshlrev_b32_e32 v240, 16, v171
	v_and_b32_e32 v241, 0xffff0000, v171
	v_pk_add_f32 v[18:19], v[18:19], v[240:241]
	s_add_u32 s42, s62, 0x20800
	s_addc_u32 s43, s63, 0
	global_load_dwordx4 v[168:171], v205, s[42:43]
	s_waitcnt vmcnt(8)
	v_lshlrev_b32_e32 v240, 16, v172
	v_and_b32_e32 v241, 0xffff0000, v172
	v_pk_add_f32 v[44:45], v[44:45], v[240:241]
	v_lshlrev_b32_e32 v240, 16, v173
	v_and_b32_e32 v241, 0xffff0000, v173
	v_pk_add_f32 v[46:47], v[46:47], v[240:241]
	v_lshlrev_b32_e32 v240, 16, v174
	v_and_b32_e32 v241, 0xffff0000, v174
	v_pk_add_f32 v[40:41], v[40:41], v[240:241]
	v_lshlrev_b32_e32 v240, 16, v175
	v_and_b32_e32 v241, 0xffff0000, v175
	v_pk_add_f32 v[42:43], v[42:43], v[240:241]
	s_add_u32 s98, s62, 0x21800
	s_addc_u32 s99, s63, 0
	global_load_dwordx4 v[172:175], v205, s[98:99]
	s_waitcnt vmcnt(8)
	v_lshlrev_b32_e32 v240, 16, v176
	v_and_b32_e32 v241, 0xffff0000, v176
	v_pk_add_f32 v[12:13], v[12:13], v[240:241]
	v_lshlrev_b32_e32 v240, 16, v177
	v_and_b32_e32 v241, 0xffff0000, v177
	v_pk_add_f32 v[14:15], v[14:15], v[240:241]
	v_lshlrev_b32_e32 v240, 16, v178
	v_and_b32_e32 v241, 0xffff0000, v178
	v_pk_add_f32 v[8:9], v[8:9], v[240:241]
	v_lshlrev_b32_e32 v240, 16, v179
	v_and_b32_e32 v241, 0xffff0000, v179
	v_pk_add_f32 v[10:11], v[10:11], v[240:241]
	s_add_u32 s42, s62, 0x20c00
	s_addc_u32 s43, s63, 0
	global_load_dwordx4 v[176:179], v205, s[42:43]
	s_waitcnt vmcnt(8)
	v_lshlrev_b32_e32 v240, 16, v180
	v_and_b32_e32 v241, 0xffff0000, v180
	v_pk_add_f32 v[36:37], v[36:37], v[240:241]
	v_lshlrev_b32_e32 v240, 16, v181
	v_and_b32_e32 v241, 0xffff0000, v181
	v_pk_add_f32 v[38:39], v[38:39], v[240:241]
	v_lshlrev_b32_e32 v240, 16, v182
	v_and_b32_e32 v241, 0xffff0000, v182
	v_pk_add_f32 v[32:33], v[32:33], v[240:241]
	v_lshlrev_b32_e32 v240, 16, v183
	v_and_b32_e32 v241, 0xffff0000, v183
	v_pk_add_f32 v[34:35], v[34:35], v[240:241]
	s_add_u32 s98, s62, 0x21c00
	s_addc_u32 s99, s63, 0
	global_load_dwordx4 v[180:183], v205, s[98:99]
	s_waitcnt vmcnt(8)
	v_lshlrev_b32_e32 v240, 16, v206
	v_and_b32_e32 v241, 0xffff0000, v206
	v_pk_add_f32 v[4:5], v[4:5], v[240:241]
	v_lshlrev_b32_e32 v240, 16, v207
	v_and_b32_e32 v241, 0xffff0000, v207
	v_pk_add_f32 v[6:7], v[6:7], v[240:241]
	v_lshlrev_b32_e32 v240, 16, v208
	v_and_b32_e32 v241, 0xffff0000, v208
	v_pk_add_f32 v[0:1], v[0:1], v[240:241]
	v_lshlrev_b32_e32 v240, 16, v209
	v_and_b32_e32 v241, 0xffff0000, v209
	v_pk_add_f32 v[2:3], v[2:3], v[240:241]
	s_add_u32 s42, s62, 0x22000
	s_addc_u32 s43, s63, 0
	global_load_dwordx4 v[206:209], v205, s[42:43]
	s_waitcnt vmcnt(8)
	v_lshlrev_b32_e32 v240, 16, v210
	v_and_b32_e32 v241, 0xffff0000, v210
	v_pk_add_f32 v[124:125], v[124:125], v[240:241]
	v_lshlrev_b32_e32 v240, 16, v211
	v_and_b32_e32 v241, 0xffff0000, v211
	v_pk_add_f32 v[126:127], v[126:127], v[240:241]
	v_lshlrev_b32_e32 v240, 16, v212
	v_and_b32_e32 v241, 0xffff0000, v212
	v_pk_add_f32 v[120:121], v[120:121], v[240:241]
	v_lshlrev_b32_e32 v240, 16, v213
	v_and_b32_e32 v241, 0xffff0000, v213
	v_pk_add_f32 v[122:123], v[122:123], v[240:241]
	s_add_u32 s98, s62, 0x23000
	s_addc_u32 s99, s63, 0
	global_load_dwordx4 v[210:213], v205, s[98:99]
	s_waitcnt vmcnt(8)
	v_lshlrev_b32_e32 v240, 16, v236
	v_and_b32_e32 v241, 0xffff0000, v236
	v_pk_add_f32 v[92:93], v[92:93], v[240:241]
	v_lshlrev_b32_e32 v240, 16, v237
	v_and_b32_e32 v241, 0xffff0000, v237
	v_pk_add_f32 v[94:95], v[94:95], v[240:241]
	v_lshlrev_b32_e32 v240, 16, v238
	v_and_b32_e32 v241, 0xffff0000, v238
	v_pk_add_f32 v[88:89], v[88:89], v[240:241]
	v_lshlrev_b32_e32 v240, 16, v239
	v_and_b32_e32 v241, 0xffff0000, v239
	v_pk_add_f32 v[90:91], v[90:91], v[240:241]
	s_add_u32 s42, s62, 0x22400
	s_addc_u32 s43, s63, 0
	global_load_dwordx4 v[236:239], v205, s[42:43]
	s_waitcnt vmcnt(8)
	v_lshlrev_b32_e32 v240, 16, v160
	v_and_b32_e32 v241, 0xffff0000, v160
	v_pk_add_f32 v[116:117], v[116:117], v[240:241]
	v_lshlrev_b32_e32 v240, 16, v161
	v_and_b32_e32 v241, 0xffff0000, v161
	v_pk_add_f32 v[118:119], v[118:119], v[240:241]
	v_lshlrev_b32_e32 v240, 16, v162
	v_and_b32_e32 v241, 0xffff0000, v162
	v_pk_add_f32 v[112:113], v[112:113], v[240:241]
	v_lshlrev_b32_e32 v240, 16, v163
	v_and_b32_e32 v241, 0xffff0000, v163
	v_pk_add_f32 v[114:115], v[114:115], v[240:241]
	s_add_u32 s98, s62, 0x23400
	s_addc_u32 s99, s63, 0
	global_load_dwordx4 v[160:163], v205, s[98:99]
	s_waitcnt vmcnt(8)
	v_lshlrev_b32_e32 v240, 16, v164
	v_and_b32_e32 v241, 0xffff0000, v164
	v_pk_add_f32 v[84:85], v[84:85], v[240:241]
	v_lshlrev_b32_e32 v240, 16, v165
	v_and_b32_e32 v241, 0xffff0000, v165
	v_pk_add_f32 v[86:87], v[86:87], v[240:241]
	v_lshlrev_b32_e32 v240, 16, v166
	v_and_b32_e32 v241, 0xffff0000, v166
	v_pk_add_f32 v[80:81], v[80:81], v[240:241]
	v_lshlrev_b32_e32 v240, 16, v167
	v_and_b32_e32 v241, 0xffff0000, v167
	v_pk_add_f32 v[82:83], v[82:83], v[240:241]
	s_add_u32 s42, s62, 0x22800
	s_addc_u32 s43, s63, 0
	global_load_dwordx4 v[164:167], v205, s[42:43]
	s_waitcnt vmcnt(8)
	v_lshlrev_b32_e32 v240, 16, v168
	v_and_b32_e32 v241, 0xffff0000, v168
	v_pk_add_f32 v[108:109], v[108:109], v[240:241]
	v_lshlrev_b32_e32 v240, 16, v169
	v_and_b32_e32 v241, 0xffff0000, v169
	v_pk_add_f32 v[110:111], v[110:111], v[240:241]
	v_lshlrev_b32_e32 v240, 16, v170
	v_and_b32_e32 v241, 0xffff0000, v170
	v_pk_add_f32 v[104:105], v[104:105], v[240:241]
	v_lshlrev_b32_e32 v240, 16, v171
	v_and_b32_e32 v241, 0xffff0000, v171
	v_pk_add_f32 v[106:107], v[106:107], v[240:241]
	s_add_u32 s98, s62, 0x23800
	s_addc_u32 s99, s63, 0
	global_load_dwordx4 v[168:171], v205, s[98:99]
	s_waitcnt vmcnt(8)
	v_lshlrev_b32_e32 v240, 16, v172
	v_and_b32_e32 v241, 0xffff0000, v172
	v_pk_add_f32 v[76:77], v[76:77], v[240:241]
	v_lshlrev_b32_e32 v240, 16, v173
	v_and_b32_e32 v241, 0xffff0000, v173
	v_pk_add_f32 v[78:79], v[78:79], v[240:241]
	v_lshlrev_b32_e32 v240, 16, v174
	v_and_b32_e32 v241, 0xffff0000, v174
	v_pk_add_f32 v[72:73], v[72:73], v[240:241]
	v_lshlrev_b32_e32 v240, 16, v175
	v_and_b32_e32 v241, 0xffff0000, v175
	v_pk_add_f32 v[74:75], v[74:75], v[240:241]
	s_add_u32 s42, s62, 0x22c00
	s_addc_u32 s43, s63, 0
	global_load_dwordx4 v[172:175], v205, s[42:43]
	s_waitcnt vmcnt(8)
	v_lshlrev_b32_e32 v240, 16, v176
	v_and_b32_e32 v241, 0xffff0000, v176
	v_pk_add_f32 v[100:101], v[100:101], v[240:241]
	v_lshlrev_b32_e32 v240, 16, v177
	v_and_b32_e32 v241, 0xffff0000, v177
	v_pk_add_f32 v[102:103], v[102:103], v[240:241]
	v_lshlrev_b32_e32 v240, 16, v178
	v_and_b32_e32 v241, 0xffff0000, v178
	v_pk_add_f32 v[96:97], v[96:97], v[240:241]
	v_lshlrev_b32_e32 v240, 16, v179
	v_and_b32_e32 v241, 0xffff0000, v179
	v_pk_add_f32 v[98:99], v[98:99], v[240:241]
	s_add_u32 s98, s62, 0x23c00
	s_addc_u32 s99, s63, 0
	global_load_dwordx4 v[176:179], v205, s[98:99]
	s_waitcnt vmcnt(8)
	v_lshlrev_b32_e32 v240, 16, v180
	v_and_b32_e32 v241, 0xffff0000, v180
	v_pk_add_f32 v[68:69], v[68:69], v[240:241]
	v_lshlrev_b32_e32 v240, 16, v181
	v_and_b32_e32 v241, 0xffff0000, v181
	v_pk_add_f32 v[70:71], v[70:71], v[240:241]
	v_lshlrev_b32_e32 v240, 16, v182
	v_and_b32_e32 v241, 0xffff0000, v182
	v_pk_add_f32 v[64:65], v[64:65], v[240:241]
	v_lshlrev_b32_e32 v240, 16, v183
	v_and_b32_e32 v241, 0xffff0000, v183
	v_pk_add_f32 v[66:67], v[66:67], v[240:241]
	s_add_u32 s42, s62, 0x40000
	s_addc_u32 s43, s63, 0
	global_load_dwordx4 v[180:183], v205, s[42:43]
	s_waitcnt vmcnt(8)
	v_lshlrev_b32_e32 v240, 16, v206
	v_and_b32_e32 v241, 0xffff0000, v206
	v_pk_add_f32 v[60:61], v[60:61], v[240:241]
	v_lshlrev_b32_e32 v240, 16, v207
	v_and_b32_e32 v241, 0xffff0000, v207
	v_pk_add_f32 v[62:63], v[62:63], v[240:241]
	v_lshlrev_b32_e32 v240, 16, v208
	v_and_b32_e32 v241, 0xffff0000, v208
	v_pk_add_f32 v[56:57], v[56:57], v[240:241]
	v_lshlrev_b32_e32 v240, 16, v209
	v_and_b32_e32 v241, 0xffff0000, v209
	v_pk_add_f32 v[58:59], v[58:59], v[240:241]
	s_add_u32 s98, s62, 0x41000
	s_addc_u32 s99, s63, 0
	global_load_dwordx4 v[206:209], v205, s[98:99]
	s_waitcnt vmcnt(8)
	v_lshlrev_b32_e32 v240, 16, v210
	v_and_b32_e32 v241, 0xffff0000, v210
	v_pk_add_f32 v[28:29], v[28:29], v[240:241]
	v_lshlrev_b32_e32 v240, 16, v211
	v_and_b32_e32 v241, 0xffff0000, v211
	v_pk_add_f32 v[30:31], v[30:31], v[240:241]
	v_lshlrev_b32_e32 v240, 16, v212
	v_and_b32_e32 v241, 0xffff0000, v212
	v_pk_add_f32 v[24:25], v[24:25], v[240:241]
	v_lshlrev_b32_e32 v240, 16, v213
	v_and_b32_e32 v241, 0xffff0000, v213
	v_pk_add_f32 v[26:27], v[26:27], v[240:241]
	s_add_u32 s42, s62, 0x40400
	s_addc_u32 s43, s63, 0
	global_load_dwordx4 v[210:213], v205, s[42:43]
	s_waitcnt vmcnt(8)
	v_lshlrev_b32_e32 v240, 16, v236
	v_and_b32_e32 v241, 0xffff0000, v236
	v_pk_add_f32 v[52:53], v[52:53], v[240:241]
	v_lshlrev_b32_e32 v240, 16, v237
	v_and_b32_e32 v241, 0xffff0000, v237
	v_pk_add_f32 v[54:55], v[54:55], v[240:241]
	v_lshlrev_b32_e32 v240, 16, v238
	v_and_b32_e32 v241, 0xffff0000, v238
	v_pk_add_f32 v[48:49], v[48:49], v[240:241]
	v_lshlrev_b32_e32 v240, 16, v239
	v_and_b32_e32 v241, 0xffff0000, v239
	v_pk_add_f32 v[50:51], v[50:51], v[240:241]
	s_add_u32 s98, s62, 0x41400
	s_addc_u32 s99, s63, 0
	global_load_dwordx4 v[236:239], v205, s[98:99]
	s_waitcnt vmcnt(8)
	v_lshlrev_b32_e32 v240, 16, v160
	v_and_b32_e32 v241, 0xffff0000, v160
	v_pk_add_f32 v[20:21], v[20:21], v[240:241]
	v_lshlrev_b32_e32 v240, 16, v161
	v_and_b32_e32 v241, 0xffff0000, v161
	v_pk_add_f32 v[22:23], v[22:23], v[240:241]
	v_lshlrev_b32_e32 v240, 16, v162
	v_and_b32_e32 v241, 0xffff0000, v162
	v_pk_add_f32 v[16:17], v[16:17], v[240:241]
	v_lshlrev_b32_e32 v240, 16, v163
	v_and_b32_e32 v241, 0xffff0000, v163
	v_pk_add_f32 v[18:19], v[18:19], v[240:241]
	s_add_u32 s42, s62, 0x40800
	s_addc_u32 s43, s63, 0
	global_load_dwordx4 v[160:163], v205, s[42:43]
	s_waitcnt vmcnt(8)
	v_lshlrev_b32_e32 v240, 16, v164
	v_and_b32_e32 v241, 0xffff0000, v164
	v_pk_add_f32 v[44:45], v[44:45], v[240:241]
	v_lshlrev_b32_e32 v240, 16, v165
	v_and_b32_e32 v241, 0xffff0000, v165
	v_pk_add_f32 v[46:47], v[46:47], v[240:241]
	v_lshlrev_b32_e32 v240, 16, v166
	v_and_b32_e32 v241, 0xffff0000, v166
	v_pk_add_f32 v[40:41], v[40:41], v[240:241]
	v_lshlrev_b32_e32 v240, 16, v167
	v_and_b32_e32 v241, 0xffff0000, v167
	v_pk_add_f32 v[42:43], v[42:43], v[240:241]
	s_add_u32 s98, s62, 0x41800
	s_addc_u32 s99, s63, 0
	global_load_dwordx4 v[164:167], v205, s[98:99]
	s_waitcnt vmcnt(8)
	v_lshlrev_b32_e32 v240, 16, v168
	v_and_b32_e32 v241, 0xffff0000, v168
	v_pk_add_f32 v[12:13], v[12:13], v[240:241]
	v_lshlrev_b32_e32 v240, 16, v169
	v_and_b32_e32 v241, 0xffff0000, v169
	v_pk_add_f32 v[14:15], v[14:15], v[240:241]
	v_lshlrev_b32_e32 v240, 16, v170
	v_and_b32_e32 v241, 0xffff0000, v170
	v_pk_add_f32 v[8:9], v[8:9], v[240:241]
	v_lshlrev_b32_e32 v240, 16, v171
	v_and_b32_e32 v241, 0xffff0000, v171
	v_pk_add_f32 v[10:11], v[10:11], v[240:241]
	s_add_u32 s42, s62, 0x40c00
	s_addc_u32 s43, s63, 0
	global_load_dwordx4 v[168:171], v205, s[42:43]
	s_waitcnt vmcnt(8)
	v_lshlrev_b32_e32 v240, 16, v172
	v_and_b32_e32 v241, 0xffff0000, v172
	v_pk_add_f32 v[36:37], v[36:37], v[240:241]
	v_lshlrev_b32_e32 v240, 16, v173
	v_and_b32_e32 v241, 0xffff0000, v173
	v_pk_add_f32 v[38:39], v[38:39], v[240:241]
	v_lshlrev_b32_e32 v240, 16, v174
	v_and_b32_e32 v241, 0xffff0000, v174
	v_pk_add_f32 v[32:33], v[32:33], v[240:241]
	v_lshlrev_b32_e32 v240, 16, v175
	v_and_b32_e32 v241, 0xffff0000, v175
	v_pk_add_f32 v[34:35], v[34:35], v[240:241]
	s_add_u32 s98, s62, 0x41c00
	s_addc_u32 s99, s63, 0
	global_load_dwordx4 v[172:175], v205, s[98:99]
	s_waitcnt vmcnt(8)
	v_lshlrev_b32_e32 v240, 16, v176
	v_and_b32_e32 v241, 0xffff0000, v176
	v_pk_add_f32 v[4:5], v[4:5], v[240:241]
	v_lshlrev_b32_e32 v240, 16, v177
	v_and_b32_e32 v241, 0xffff0000, v177
	v_pk_add_f32 v[6:7], v[6:7], v[240:241]
	v_lshlrev_b32_e32 v240, 16, v178
	v_and_b32_e32 v241, 0xffff0000, v178
	v_pk_add_f32 v[0:1], v[0:1], v[240:241]
	v_lshlrev_b32_e32 v240, 16, v179
	v_and_b32_e32 v241, 0xffff0000, v179
	v_pk_add_f32 v[2:3], v[2:3], v[240:241]
	s_add_u32 s42, s62, 0x42000
	s_addc_u32 s43, s63, 0
	global_load_dwordx4 v[176:179], v205, s[42:43]
	s_waitcnt vmcnt(8)
	v_lshlrev_b32_e32 v240, 16, v180
	v_and_b32_e32 v241, 0xffff0000, v180
	v_pk_add_f32 v[124:125], v[124:125], v[240:241]
	v_lshlrev_b32_e32 v240, 16, v181
	v_and_b32_e32 v241, 0xffff0000, v181
	v_pk_add_f32 v[126:127], v[126:127], v[240:241]
	v_lshlrev_b32_e32 v240, 16, v182
	v_and_b32_e32 v241, 0xffff0000, v182
	v_pk_add_f32 v[120:121], v[120:121], v[240:241]
	v_lshlrev_b32_e32 v240, 16, v183
	v_and_b32_e32 v241, 0xffff0000, v183
	v_pk_add_f32 v[122:123], v[122:123], v[240:241]
	s_add_u32 s98, s62, 0x43000
	s_addc_u32 s99, s63, 0
	global_load_dwordx4 v[180:183], v205, s[98:99]
	s_waitcnt vmcnt(8)
	v_lshlrev_b32_e32 v240, 16, v206
	v_and_b32_e32 v241, 0xffff0000, v206
	v_pk_add_f32 v[92:93], v[92:93], v[240:241]
	v_lshlrev_b32_e32 v240, 16, v207
	v_and_b32_e32 v241, 0xffff0000, v207
	v_pk_add_f32 v[94:95], v[94:95], v[240:241]
	v_lshlrev_b32_e32 v240, 16, v208
	v_and_b32_e32 v241, 0xffff0000, v208
	v_pk_add_f32 v[88:89], v[88:89], v[240:241]
	v_lshlrev_b32_e32 v240, 16, v209
	v_and_b32_e32 v241, 0xffff0000, v209
	v_pk_add_f32 v[90:91], v[90:91], v[240:241]
	s_add_u32 s42, s62, 0x42400
	s_addc_u32 s43, s63, 0
	global_load_dwordx4 v[206:209], v205, s[42:43]
	s_waitcnt vmcnt(8)
	v_lshlrev_b32_e32 v240, 16, v210
	v_and_b32_e32 v241, 0xffff0000, v210
	v_pk_add_f32 v[116:117], v[116:117], v[240:241]
	v_lshlrev_b32_e32 v240, 16, v211
	v_and_b32_e32 v241, 0xffff0000, v211
	v_pk_add_f32 v[118:119], v[118:119], v[240:241]
	v_lshlrev_b32_e32 v240, 16, v212
	v_and_b32_e32 v241, 0xffff0000, v212
	v_pk_add_f32 v[112:113], v[112:113], v[240:241]
	v_lshlrev_b32_e32 v240, 16, v213
	v_and_b32_e32 v241, 0xffff0000, v213
	v_pk_add_f32 v[114:115], v[114:115], v[240:241]
	s_add_u32 s98, s62, 0x43400
	s_addc_u32 s99, s63, 0
	global_load_dwordx4 v[210:213], v205, s[98:99]
	s_waitcnt vmcnt(8)
	v_lshlrev_b32_e32 v240, 16, v236
	v_and_b32_e32 v241, 0xffff0000, v236
	v_pk_add_f32 v[84:85], v[84:85], v[240:241]
	v_lshlrev_b32_e32 v240, 16, v237
	v_and_b32_e32 v241, 0xffff0000, v237
	v_pk_add_f32 v[86:87], v[86:87], v[240:241]
	v_lshlrev_b32_e32 v240, 16, v238
	v_and_b32_e32 v241, 0xffff0000, v238
	v_pk_add_f32 v[80:81], v[80:81], v[240:241]
	v_lshlrev_b32_e32 v240, 16, v239
	v_and_b32_e32 v241, 0xffff0000, v239
	v_pk_add_f32 v[82:83], v[82:83], v[240:241]
	s_add_u32 s42, s62, 0x42800
	s_addc_u32 s43, s63, 0
	global_load_dwordx4 v[236:239], v205, s[42:43]
	s_waitcnt vmcnt(8)
	v_lshlrev_b32_e32 v240, 16, v160
	v_and_b32_e32 v241, 0xffff0000, v160
	v_pk_add_f32 v[108:109], v[108:109], v[240:241]
	v_lshlrev_b32_e32 v240, 16, v161
	v_and_b32_e32 v241, 0xffff0000, v161
	v_pk_add_f32 v[110:111], v[110:111], v[240:241]
	v_lshlrev_b32_e32 v240, 16, v162
	v_and_b32_e32 v241, 0xffff0000, v162
	v_pk_add_f32 v[104:105], v[104:105], v[240:241]
	v_lshlrev_b32_e32 v240, 16, v163
	v_and_b32_e32 v241, 0xffff0000, v163
	v_pk_add_f32 v[106:107], v[106:107], v[240:241]
	s_add_u32 s98, s62, 0x43800
	s_addc_u32 s99, s63, 0
	global_load_dwordx4 v[160:163], v205, s[98:99]
	s_waitcnt vmcnt(8)
	v_lshlrev_b32_e32 v240, 16, v164
	v_and_b32_e32 v241, 0xffff0000, v164
	v_pk_add_f32 v[76:77], v[76:77], v[240:241]
	v_lshlrev_b32_e32 v240, 16, v165
	v_and_b32_e32 v241, 0xffff0000, v165
	v_pk_add_f32 v[78:79], v[78:79], v[240:241]
	v_lshlrev_b32_e32 v240, 16, v166
	v_and_b32_e32 v241, 0xffff0000, v166
	v_pk_add_f32 v[72:73], v[72:73], v[240:241]
	v_lshlrev_b32_e32 v240, 16, v167
	v_and_b32_e32 v241, 0xffff0000, v167
	v_pk_add_f32 v[74:75], v[74:75], v[240:241]
	s_add_u32 s42, s62, 0x42c00
	s_addc_u32 s43, s63, 0
	global_load_dwordx4 v[164:167], v205, s[42:43]
	s_waitcnt vmcnt(8)
	v_lshlrev_b32_e32 v240, 16, v168
	v_and_b32_e32 v241, 0xffff0000, v168
	v_pk_add_f32 v[100:101], v[100:101], v[240:241]
	v_lshlrev_b32_e32 v240, 16, v169
	v_and_b32_e32 v241, 0xffff0000, v169
	v_pk_add_f32 v[102:103], v[102:103], v[240:241]
	v_lshlrev_b32_e32 v240, 16, v170
	v_and_b32_e32 v241, 0xffff0000, v170
	v_pk_add_f32 v[96:97], v[96:97], v[240:241]
	v_lshlrev_b32_e32 v240, 16, v171
	v_and_b32_e32 v241, 0xffff0000, v171
	v_pk_add_f32 v[98:99], v[98:99], v[240:241]
	s_add_u32 s98, s62, 0x43c00
	s_addc_u32 s99, s63, 0
	global_load_dwordx4 v[168:171], v205, s[98:99]
	s_waitcnt vmcnt(8)
	v_lshlrev_b32_e32 v240, 16, v172
	v_and_b32_e32 v241, 0xffff0000, v172
	v_pk_add_f32 v[68:69], v[68:69], v[240:241]
	v_lshlrev_b32_e32 v240, 16, v173
	v_and_b32_e32 v241, 0xffff0000, v173
	v_pk_add_f32 v[70:71], v[70:71], v[240:241]
	v_lshlrev_b32_e32 v240, 16, v174
	v_and_b32_e32 v241, 0xffff0000, v174
	v_pk_add_f32 v[64:65], v[64:65], v[240:241]
	v_lshlrev_b32_e32 v240, 16, v175
	v_and_b32_e32 v241, 0xffff0000, v175
	v_pk_add_f32 v[66:67], v[66:67], v[240:241]
	s_add_u32 s42, s10, 0x0
	s_addc_u32 s43, s11, 0
	global_load_dwordx4 v[172:175], v203, s[42:43]
	s_waitcnt vmcnt(8)
	v_lshlrev_b32_e32 v240, 16, v176
	v_and_b32_e32 v241, 0xffff0000, v176
	v_pk_add_f32 v[60:61], v[60:61], v[240:241]
	v_lshlrev_b32_e32 v240, 16, v177
	v_and_b32_e32 v241, 0xffff0000, v177
	v_pk_add_f32 v[62:63], v[62:63], v[240:241]
	v_lshlrev_b32_e32 v240, 16, v178
	v_and_b32_e32 v241, 0xffff0000, v178
	v_pk_add_f32 v[56:57], v[56:57], v[240:241]
	v_lshlrev_b32_e32 v240, 16, v179
	v_and_b32_e32 v241, 0xffff0000, v179
	v_pk_add_f32 v[58:59], v[58:59], v[240:241]
	s_add_u32 s98, s10, 0x0
	s_addc_u32 s99, s11, 0
	global_load_dwordx4 v[176:179], v203, s[98:99] offset:16
	s_waitcnt vmcnt(8)
	v_lshlrev_b32_e32 v240, 16, v180
	v_and_b32_e32 v241, 0xffff0000, v180
	v_pk_add_f32 v[28:29], v[28:29], v[240:241]
	v_lshlrev_b32_e32 v240, 16, v181
	v_and_b32_e32 v241, 0xffff0000, v181
	v_pk_add_f32 v[30:31], v[30:31], v[240:241]
	v_lshlrev_b32_e32 v240, 16, v182
	v_and_b32_e32 v241, 0xffff0000, v182
	v_pk_add_f32 v[24:25], v[24:25], v[240:241]
	v_lshlrev_b32_e32 v240, 16, v183
	v_and_b32_e32 v241, 0xffff0000, v183
	v_pk_add_f32 v[26:27], v[26:27], v[240:241]
	s_add_u32 s42, s10, 0x200
	s_addc_u32 s43, s11, 0
	global_load_dwordx4 v[180:183], v203, s[42:43]
	s_waitcnt vmcnt(8)
	v_lshlrev_b32_e32 v240, 16, v206
	v_and_b32_e32 v241, 0xffff0000, v206
	v_pk_add_f32 v[52:53], v[52:53], v[240:241]
	v_lshlrev_b32_e32 v240, 16, v207
	v_and_b32_e32 v241, 0xffff0000, v207
	v_pk_add_f32 v[54:55], v[54:55], v[240:241]
	v_lshlrev_b32_e32 v240, 16, v208
	v_and_b32_e32 v241, 0xffff0000, v208
	v_pk_add_f32 v[48:49], v[48:49], v[240:241]
	v_lshlrev_b32_e32 v240, 16, v209
	v_and_b32_e32 v241, 0xffff0000, v209
	v_pk_add_f32 v[50:51], v[50:51], v[240:241]
	s_add_u32 s98, s10, 0x200
	s_addc_u32 s99, s11, 0
	global_load_dwordx4 v[206:209], v203, s[98:99] offset:16
	s_waitcnt vmcnt(8)
	v_lshlrev_b32_e32 v240, 16, v210
	v_and_b32_e32 v241, 0xffff0000, v210
	v_pk_add_f32 v[20:21], v[20:21], v[240:241]
	v_lshlrev_b32_e32 v240, 16, v211
	v_and_b32_e32 v241, 0xffff0000, v211
	v_pk_add_f32 v[22:23], v[22:23], v[240:241]
	v_lshlrev_b32_e32 v240, 16, v212
	v_and_b32_e32 v241, 0xffff0000, v212
	v_pk_add_f32 v[16:17], v[16:17], v[240:241]
	v_lshlrev_b32_e32 v240, 16, v213
	v_and_b32_e32 v241, 0xffff0000, v213
	v_pk_add_f32 v[18:19], v[18:19], v[240:241]
	s_add_u32 s42, s10, 0x10000
	s_addc_u32 s43, s11, 0
	global_load_dwordx4 v[210:213], v203, s[42:43]
	s_waitcnt vmcnt(8)
	v_lshlrev_b32_e32 v240, 16, v236
	v_and_b32_e32 v241, 0xffff0000, v236
	v_pk_add_f32 v[44:45], v[44:45], v[240:241]
	v_lshlrev_b32_e32 v240, 16, v237
	v_and_b32_e32 v241, 0xffff0000, v237
	v_pk_add_f32 v[46:47], v[46:47], v[240:241]
	v_lshlrev_b32_e32 v240, 16, v238
	v_and_b32_e32 v241, 0xffff0000, v238
	v_pk_add_f32 v[40:41], v[40:41], v[240:241]
	v_lshlrev_b32_e32 v240, 16, v239
	v_and_b32_e32 v241, 0xffff0000, v239
	v_pk_add_f32 v[42:43], v[42:43], v[240:241]
	s_add_u32 s98, s10, 0x10000
	s_addc_u32 s99, s11, 0
	global_load_dwordx4 v[236:239], v203, s[98:99] offset:16
	s_waitcnt vmcnt(8)
	v_lshlrev_b32_e32 v240, 16, v160
	v_and_b32_e32 v241, 0xffff0000, v160
	v_pk_add_f32 v[12:13], v[12:13], v[240:241]
	v_lshlrev_b32_e32 v240, 16, v161
	v_and_b32_e32 v241, 0xffff0000, v161
	v_pk_add_f32 v[14:15], v[14:15], v[240:241]
	v_lshlrev_b32_e32 v240, 16, v162
	v_and_b32_e32 v241, 0xffff0000, v162
	v_pk_add_f32 v[8:9], v[8:9], v[240:241]
	v_lshlrev_b32_e32 v240, 16, v163
	v_and_b32_e32 v241, 0xffff0000, v163
	v_pk_add_f32 v[10:11], v[10:11], v[240:241]
	s_add_u32 s42, s10, 0x10200
	s_addc_u32 s43, s11, 0
	global_load_dwordx4 v[160:163], v203, s[42:43]
	s_waitcnt vmcnt(8)
	v_lshlrev_b32_e32 v240, 16, v164
	v_and_b32_e32 v241, 0xffff0000, v164
	v_pk_add_f32 v[36:37], v[36:37], v[240:241]
	v_lshlrev_b32_e32 v240, 16, v165
	v_and_b32_e32 v241, 0xffff0000, v165
	v_pk_add_f32 v[38:39], v[38:39], v[240:241]
	v_lshlrev_b32_e32 v240, 16, v166
	v_and_b32_e32 v241, 0xffff0000, v166
	v_pk_add_f32 v[32:33], v[32:33], v[240:241]
	v_lshlrev_b32_e32 v240, 16, v167
	v_and_b32_e32 v241, 0xffff0000, v167
	v_pk_add_f32 v[34:35], v[34:35], v[240:241]
	s_add_u32 s98, s10, 0x10200
	s_addc_u32 s99, s11, 0
	global_load_dwordx4 v[164:167], v203, s[98:99] offset:16
	s_waitcnt vmcnt(8)
	v_lshlrev_b32_e32 v240, 16, v168
	v_and_b32_e32 v241, 0xffff0000, v168
	v_pk_add_f32 v[4:5], v[4:5], v[240:241]
	v_lshlrev_b32_e32 v240, 16, v169
	v_and_b32_e32 v241, 0xffff0000, v169
	v_pk_add_f32 v[6:7], v[6:7], v[240:241]
	v_lshlrev_b32_e32 v240, 16, v170
	v_and_b32_e32 v241, 0xffff0000, v170
	v_pk_add_f32 v[0:1], v[0:1], v[240:241]
	v_lshlrev_b32_e32 v240, 16, v171
	v_and_b32_e32 v241, 0xffff0000, v171
	v_pk_add_f32 v[2:3], v[2:3], v[240:241]
	s_add_u32 s42, s10, 0x20000
	s_addc_u32 s43, s11, 0
	global_load_dwordx4 v[168:171], v203, s[42:43]
	s_waitcnt vmcnt(8)
	v_pk_fma_f32 v[124:125], v[148:149], v[124:125], v[172:173]
	v_pk_fma_f32 v[126:127], v[150:151], v[126:127], v[174:175]
	s_add_u32 s98, s10, 0x0
	s_addc_u32 s99, s11, 0
	global_store_dwordx4 v203, v[124:127], s[98:99]
	s_add_u32 s42, s10, 0x20000
	s_addc_u32 s43, s11, 0
	global_load_dwordx4 v[172:175], v203, s[42:43] offset:16
	s_waitcnt vmcnt(9)
	v_pk_fma_f32 v[120:121], v[144:145], v[120:121], v[176:177]
	v_pk_fma_f32 v[122:123], v[146:147], v[122:123], v[178:179]
	s_add_u32 s98, s10, 0x0
	s_addc_u32 s99, s11, 0
	global_store_dwordx4 v203, v[120:123], s[98:99] offset:16
	s_add_u32 s42, s10, 0x20200
	s_addc_u32 s43, s11, 0
	global_load_dwordx4 v[176:179], v203, s[42:43]
	s_waitcnt vmcnt(10)
	v_pk_fma_f32 v[92:93], v[156:157], v[92:93], v[180:181]
	v_pk_fma_f32 v[94:95], v[158:159], v[94:95], v[182:183]
	s_add_u32 s98, s10, 0x200
	s_addc_u32 s99, s11, 0
	global_store_dwordx4 v203, v[92:95], s[98:99]
	s_add_u32 s42, s10, 0x20200
	s_addc_u32 s43, s11, 0
	global_load_dwordx4 v[180:183], v203, s[42:43] offset:16
	s_waitcnt vmcnt(11)
	v_pk_fma_f32 v[88:89], v[152:153], v[88:89], v[206:207]
	v_pk_fma_f32 v[90:91], v[154:155], v[90:91], v[208:209]
	s_add_u32 s98, s10, 0x200
	s_addc_u32 s99, s11, 0
	global_store_dwordx4 v203, v[88:91], s[98:99] offset:16
	s_add_u32 s42, s10, 0x30000
	s_addc_u32 s43, s11, 0
	global_load_dwordx4 v[206:209], v203, s[42:43]
	s_waitcnt vmcnt(12)
	v_pk_fma_f32 v[116:117], v[148:149], v[116:117], v[210:211]
	v_pk_fma_f32 v[118:119], v[150:151], v[118:119], v[212:213]
	s_add_u32 s98, s10, 0x10000
	s_addc_u32 s99, s11, 0
	global_store_dwordx4 v203, v[116:119], s[98:99]
	s_add_u32 s42, s10, 0x30000
	s_addc_u32 s43, s11, 0
	global_load_dwordx4 v[210:213], v203, s[42:43] offset:16
	s_waitcnt vmcnt(13)
	v_pk_fma_f32 v[112:113], v[144:145], v[112:113], v[236:237]
	v_pk_fma_f32 v[114:115], v[146:147], v[114:115], v[238:239]
	s_add_u32 s98, s10, 0x10000
	s_addc_u32 s99, s11, 0
	global_store_dwordx4 v203, v[112:115], s[98:99] offset:16
	s_add_u32 s42, s10, 0x30200
	s_addc_u32 s43, s11, 0
	global_load_dwordx4 v[236:239], v203, s[42:43]
	s_waitcnt vmcnt(14)
	v_pk_fma_f32 v[84:85], v[156:157], v[84:85], v[160:161]
	v_pk_fma_f32 v[86:87], v[158:159], v[86:87], v[162:163]
	s_add_u32 s98, s10, 0x10200
	s_addc_u32 s99, s11, 0
	global_store_dwordx4 v203, v[84:87], s[98:99]
	s_add_u32 s42, s10, 0x30200
	s_addc_u32 s43, s11, 0
	global_load_dwordx4 v[160:163], v203, s[42:43] offset:16
	s_waitcnt vmcnt(15)
	v_pk_fma_f32 v[80:81], v[152:153], v[80:81], v[164:165]
	v_pk_fma_f32 v[82:83], v[154:155], v[82:83], v[166:167]
	s_add_u32 s98, s10, 0x10200
	s_addc_u32 s99, s11, 0
	global_store_dwordx4 v203, v[80:83], s[98:99] offset:16
	s_add_u32 s42, s10, 0x80000
	s_addc_u32 s43, s11, 0
	global_load_dwordx4 v[164:167], v203, s[42:43]
	s_waitcnt vmcnt(16)
	v_pk_fma_f32 v[108:109], v[148:149], v[108:109], v[168:169]
	v_pk_fma_f32 v[110:111], v[150:151], v[110:111], v[170:171]
	s_add_u32 s98, s10, 0x20000
	s_addc_u32 s99, s11, 0
	global_store_dwordx4 v203, v[108:111], s[98:99]
	s_add_u32 s42, s10, 0x80000
	s_addc_u32 s43, s11, 0
	global_load_dwordx4 v[168:171], v203, s[42:43] offset:16
	s_waitcnt vmcnt(16)
	v_pk_fma_f32 v[104:105], v[144:145], v[104:105], v[172:173]
	v_pk_fma_f32 v[106:107], v[146:147], v[106:107], v[174:175]
	s_add_u32 s98, s10, 0x20000
	s_addc_u32 s99, s11, 0
	global_store_dwordx4 v203, v[104:107], s[98:99] offset:16
	s_add_u32 s42, s10, 0x80200
	s_addc_u32 s43, s11, 0
	global_load_dwordx4 v[172:175], v203, s[42:43]
	s_waitcnt vmcnt(16)
	v_pk_fma_f32 v[76:77], v[156:157], v[76:77], v[176:177]
	v_pk_fma_f32 v[78:79], v[158:159], v[78:79], v[178:179]
	s_add_u32 s98, s10, 0x20200
	s_addc_u32 s99, s11, 0
	global_store_dwordx4 v203, v[76:79], s[98:99]
	s_add_u32 s42, s10, 0x80200
	s_addc_u32 s43, s11, 0
	global_load_dwordx4 v[176:179], v203, s[42:43] offset:16
	s_waitcnt vmcnt(16)
	v_pk_fma_f32 v[72:73], v[152:153], v[72:73], v[180:181]
	v_pk_fma_f32 v[74:75], v[154:155], v[74:75], v[182:183]
	s_add_u32 s98, s10, 0x20200
	s_addc_u32 s99, s11, 0
	global_store_dwordx4 v203, v[72:75], s[98:99] offset:16
	s_add_u32 s42, s10, 0x90000
	s_addc_u32 s43, s11, 0
	global_load_dwordx4 v[180:183], v203, s[42:43]
	s_waitcnt vmcnt(16)
	v_pk_fma_f32 v[100:101], v[148:149], v[100:101], v[206:207]
	v_pk_fma_f32 v[102:103], v[150:151], v[102:103], v[208:209]
	s_add_u32 s98, s10, 0x30000
	s_addc_u32 s99, s11, 0
	global_store_dwordx4 v203, v[100:103], s[98:99]
	s_add_u32 s42, s10, 0x90000
	s_addc_u32 s43, s11, 0
	global_load_dwordx4 v[206:209], v203, s[42:43] offset:16
	s_waitcnt vmcnt(16)
	v_pk_fma_f32 v[96:97], v[144:145], v[96:97], v[210:211]
	v_pk_fma_f32 v[98:99], v[146:147], v[98:99], v[212:213]
	s_add_u32 s98, s10, 0x30000
	s_addc_u32 s99, s11, 0
	global_store_dwordx4 v203, v[96:99], s[98:99] offset:16
	s_add_u32 s42, s10, 0x90200
	s_addc_u32 s43, s11, 0
	global_load_dwordx4 v[210:213], v203, s[42:43]
	s_waitcnt vmcnt(16)
	v_pk_fma_f32 v[68:69], v[156:157], v[68:69], v[236:237]
	v_pk_fma_f32 v[70:71], v[158:159], v[70:71], v[238:239]
	s_add_u32 s98, s10, 0x30200
	s_addc_u32 s99, s11, 0
	global_store_dwordx4 v203, v[68:71], s[98:99]
	s_add_u32 s42, s10, 0x90200
	s_addc_u32 s43, s11, 0
	global_load_dwordx4 v[236:239], v203, s[42:43] offset:16
	s_waitcnt vmcnt(16)
	v_pk_fma_f32 v[64:65], v[152:153], v[64:65], v[160:161]
	v_pk_fma_f32 v[66:67], v[154:155], v[66:67], v[162:163]
	s_add_u32 s98, s10, 0x30200
	s_addc_u32 s99, s11, 0
	global_store_dwordx4 v203, v[64:67], s[98:99] offset:16
	s_add_u32 s42, s10, 0xa0000
	s_addc_u32 s43, s11, 0
	global_load_dwordx4 v[160:163], v203, s[42:43]
	s_waitcnt vmcnt(16)
	v_pk_fma_f32 v[60:61], v[148:149], v[60:61], v[164:165]
	v_pk_fma_f32 v[62:63], v[150:151], v[62:63], v[166:167]
	s_add_u32 s98, s10, 0x80000
	s_addc_u32 s99, s11, 0
	global_store_dwordx4 v203, v[60:63], s[98:99]
	s_add_u32 s42, s10, 0xa0000
	s_addc_u32 s43, s11, 0
	global_load_dwordx4 v[164:167], v203, s[42:43] offset:16
	s_waitcnt vmcnt(16)
	v_pk_fma_f32 v[56:57], v[144:145], v[56:57], v[168:169]
	v_pk_fma_f32 v[58:59], v[146:147], v[58:59], v[170:171]
	s_add_u32 s98, s10, 0x80000
	s_addc_u32 s99, s11, 0
	global_store_dwordx4 v203, v[56:59], s[98:99] offset:16
	s_add_u32 s42, s10, 0xa0200
	s_addc_u32 s43, s11, 0
	global_load_dwordx4 v[168:171], v203, s[42:43]
	s_waitcnt vmcnt(16)
	v_pk_fma_f32 v[28:29], v[156:157], v[28:29], v[172:173]
	v_pk_fma_f32 v[30:31], v[158:159], v[30:31], v[174:175]
	s_add_u32 s98, s10, 0x80200
	s_addc_u32 s99, s11, 0
	global_store_dwordx4 v203, v[28:31], s[98:99]
	s_add_u32 s42, s10, 0xa0200
	s_addc_u32 s43, s11, 0
	global_load_dwordx4 v[172:175], v203, s[42:43] offset:16
	s_waitcnt vmcnt(16)
	v_pk_fma_f32 v[24:25], v[152:153], v[24:25], v[176:177]
	v_pk_fma_f32 v[26:27], v[154:155], v[26:27], v[178:179]
	s_add_u32 s98, s10, 0x80200
	s_addc_u32 s99, s11, 0
	global_store_dwordx4 v203, v[24:27], s[98:99] offset:16
	s_waitcnt vmcnt(15)
	v_pk_fma_f32 v[52:53], v[148:149], v[52:53], v[180:181]
	v_pk_fma_f32 v[54:55], v[150:151], v[54:55], v[182:183]
	s_add_u32 s42, s10, 0x90000
	s_addc_u32 s43, s11, 0
	global_store_dwordx4 v203, v[52:55], s[42:43]
	s_waitcnt vmcnt(14)
	v_pk_fma_f32 v[48:49], v[144:145], v[48:49], v[206:207]
	v_pk_fma_f32 v[50:51], v[146:147], v[50:51], v[208:209]
	s_add_u32 s98, s10, 0x90000
	s_addc_u32 s99, s11, 0
	global_store_dwordx4 v203, v[48:51], s[98:99] offset:16
	s_waitcnt vmcnt(13)
	v_pk_fma_f32 v[20:21], v[156:157], v[20:21], v[210:211]
	v_pk_fma_f32 v[22:23], v[158:159], v[22:23], v[212:213]
	s_add_u32 s42, s10, 0x90200
	s_addc_u32 s43, s11, 0
	global_store_dwordx4 v203, v[20:23], s[42:43]
	s_waitcnt vmcnt(12)
	v_pk_fma_f32 v[16:17], v[152:153], v[16:17], v[236:237]
	v_pk_fma_f32 v[18:19], v[154:155], v[18:19], v[238:239]
	s_add_u32 s98, s10, 0x90200
	s_addc_u32 s99, s11, 0
	global_store_dwordx4 v203, v[16:19], s[98:99] offset:16
	s_waitcnt vmcnt(11)
	v_pk_fma_f32 v[44:45], v[148:149], v[44:45], v[160:161]
	v_pk_fma_f32 v[46:47], v[150:151], v[46:47], v[162:163]
	s_add_u32 s42, s10, 0xa0000
	s_addc_u32 s43, s11, 0
	global_store_dwordx4 v203, v[44:47], s[42:43]
	s_waitcnt vmcnt(10)
	v_pk_fma_f32 v[40:41], v[144:145], v[40:41], v[164:165]
	v_pk_fma_f32 v[42:43], v[146:147], v[42:43], v[166:167]
	s_add_u32 s98, s10, 0xa0000
	s_addc_u32 s99, s11, 0
	global_store_dwordx4 v203, v[40:43], s[98:99] offset:16
	s_waitcnt vmcnt(9)
	v_pk_fma_f32 v[12:13], v[156:157], v[12:13], v[168:169]
	v_pk_fma_f32 v[14:15], v[158:159], v[14:15], v[170:171]
	s_add_u32 s42, s10, 0xa0200
	s_addc_u32 s43, s11, 0
	global_store_dwordx4 v203, v[12:15], s[42:43]
	s_waitcnt vmcnt(8)
	v_pk_fma_f32 v[8:9], v[152:153], v[8:9], v[172:173]
	v_pk_fma_f32 v[10:11], v[154:155], v[10:11], v[174:175]
	s_add_u32 s98, s10, 0xa0200
	s_addc_u32 s99, s11, 0
	global_store_dwordx4 v203, v[8:11], s[98:99] offset:16
	s_branch .Lfq_predone
.Lfq_np2:
	s_add_u32 s42, s62, 0x0
	s_addc_u32 s43, s63, 0
	global_load_dwordx4 v[160:163], v205, s[42:43]
	s_add_u32 s98, s62, 0x1000
	s_addc_u32 s99, s63, 0
	global_load_dwordx4 v[164:167], v205, s[98:99]
	s_add_u32 s42, s62, 0x400
	s_addc_u32 s43, s63, 0
	global_load_dwordx4 v[168:171], v205, s[42:43]
	s_add_u32 s98, s62, 0x1400
	s_addc_u32 s99, s63, 0
	global_load_dwordx4 v[172:175], v205, s[98:99]
	s_add_u32 s42, s62, 0x800
	s_addc_u32 s43, s63, 0
	global_load_dwordx4 v[176:179], v205, s[42:43]
	s_add_u32 s98, s62, 0x1800
	s_addc_u32 s99, s63, 0
	global_load_dwordx4 v[180:183], v205, s[98:99]
	s_add_u32 s42, s62, 0xc00
	s_addc_u32 s43, s63, 0
	global_load_dwordx4 v[206:209], v205, s[42:43]
	s_add_u32 s98, s62, 0x1c00
	s_addc_u32 s99, s63, 0
	global_load_dwordx4 v[210:213], v205, s[98:99]
	s_add_u32 s42, s62, 0x2000
	s_addc_u32 s43, s63, 0
	global_load_dwordx4 v[236:239], v205, s[42:43]
	s_waitcnt vmcnt(8)
	v_lshlrev_b32_e32 v240, 16, v160
	v_and_b32_e32 v241, 0xffff0000, v160
	v_pk_add_f32 v[124:125], v[124:125], v[240:241]
	v_lshlrev_b32_e32 v240, 16, v161
	v_and_b32_e32 v241, 0xffff0000, v161
	v_pk_add_f32 v[126:127], v[126:127], v[240:241]
	v_lshlrev_b32_e32 v240, 16, v162
	v_and_b32_e32 v241, 0xffff0000, v162
	v_pk_add_f32 v[120:121], v[120:121], v[240:241]
	v_lshlrev_b32_e32 v240, 16, v163
	v_and_b32_e32 v241, 0xffff0000, v163
	v_pk_add_f32 v[122:123], v[122:123], v[240:241]
	s_add_u32 s98, s62, 0x3000
	s_addc_u32 s99, s63, 0
	global_load_dwordx4 v[160:163], v205, s[98:99]
	s_waitcnt vmcnt(8)
	v_lshlrev_b32_e32 v240, 16, v164
	v_and_b32_e32 v241, 0xffff0000, v164
	v_pk_add_f32 v[92:93], v[92:93], v[240:241]
	v_lshlrev_b32_e32 v240, 16, v165
	v_and_b32_e32 v241, 0xffff0000, v165
	v_pk_add_f32 v[94:95], v[94:95], v[240:241]
	v_lshlrev_b32_e32 v240, 16, v166
	v_and_b32_e32 v241, 0xffff0000, v166
	v_pk_add_f32 v[88:89], v[88:89], v[240:241]
	v_lshlrev_b32_e32 v240, 16, v167
	v_and_b32_e32 v241, 0xffff0000, v167
	v_pk_add_f32 v[90:91], v[90:91], v[240:241]
	s_add_u32 s42, s62, 0x2400
	s_addc_u32 s43, s63, 0
	global_load_dwordx4 v[164:167], v205, s[42:43]
	s_waitcnt vmcnt(8)
	v_lshlrev_b32_e32 v240, 16, v168
	v_and_b32_e32 v241, 0xffff0000, v168
	v_pk_add_f32 v[116:117], v[116:117], v[240:241]
	v_lshlrev_b32_e32 v240, 16, v169
	v_and_b32_e32 v241, 0xffff0000, v169
	v_pk_add_f32 v[118:119], v[118:119], v[240:241]
	v_lshlrev_b32_e32 v240, 16, v170
	v_and_b32_e32 v241, 0xffff0000, v170
	v_pk_add_f32 v[112:113], v[112:113], v[240:241]
	v_lshlrev_b32_e32 v240, 16, v171
	v_and_b32_e32 v241, 0xffff0000, v171
	v_pk_add_f32 v[114:115], v[114:115], v[240:241]
	s_add_u32 s98, s62, 0x3400
	s_addc_u32 s99, s63, 0
	global_load_dwordx4 v[168:171], v205, s[98:99]
	s_waitcnt vmcnt(8)
	v_lshlrev_b32_e32 v240, 16, v172
	v_and_b32_e32 v241, 0xffff0000, v172
	v_pk_add_f32 v[84:85], v[84:85], v[240:241]
	v_lshlrev_b32_e32 v240, 16, v173
	v_and_b32_e32 v241, 0xffff0000, v173
	v_pk_add_f32 v[86:87], v[86:87], v[240:241]
	v_lshlrev_b32_e32 v240, 16, v174
	v_and_b32_e32 v241, 0xffff0000, v174
	v_pk_add_f32 v[80:81], v[80:81], v[240:241]
	v_lshlrev_b32_e32 v240, 16, v175
	v_and_b32_e32 v241, 0xffff0000, v175
	v_pk_add_f32 v[82:83], v[82:83], v[240:241]
	s_add_u32 s42, s62, 0x2800
	s_addc_u32 s43, s63, 0
	global_load_dwordx4 v[172:175], v205, s[42:43]
	s_waitcnt vmcnt(8)
	v_lshlrev_b32_e32 v240, 16, v176
	v_and_b32_e32 v241, 0xffff0000, v176
	v_pk_add_f32 v[108:109], v[108:109], v[240:241]
	v_lshlrev_b32_e32 v240, 16, v177
	v_and_b32_e32 v241, 0xffff0000, v177
	v_pk_add_f32 v[110:111], v[110:111], v[240:241]
	v_lshlrev_b32_e32 v240, 16, v178
	v_and_b32_e32 v241, 0xffff0000, v178
	v_pk_add_f32 v[104:105], v[104:105], v[240:241]
	v_lshlrev_b32_e32 v240, 16, v179
	v_and_b32_e32 v241, 0xffff0000, v179
	v_pk_add_f32 v[106:107], v[106:107], v[240:241]
	s_add_u32 s98, s62, 0x3800
	s_addc_u32 s99, s63, 0
	global_load_dwordx4 v[176:179], v205, s[98:99]
	s_waitcnt vmcnt(8)
	v_lshlrev_b32_e32 v240, 16, v180
	v_and_b32_e32 v241, 0xffff0000, v180
	v_pk_add_f32 v[76:77], v[76:77], v[240:241]
	v_lshlrev_b32_e32 v240, 16, v181
	v_and_b32_e32 v241, 0xffff0000, v181
	v_pk_add_f32 v[78:79], v[78:79], v[240:241]
	v_lshlrev_b32_e32 v240, 16, v182
	v_and_b32_e32 v241, 0xffff0000, v182
	v_pk_add_f32 v[72:73], v[72:73], v[240:241]
	v_lshlrev_b32_e32 v240, 16, v183
	v_and_b32_e32 v241, 0xffff0000, v183
	v_pk_add_f32 v[74:75], v[74:75], v[240:241]
	s_add_u32 s42, s62, 0x2c00
	s_addc_u32 s43, s63, 0
	global_load_dwordx4 v[180:183], v205, s[42:43]
	s_waitcnt vmcnt(8)
	v_lshlrev_b32_e32 v240, 16, v206
	v_and_b32_e32 v241, 0xffff0000, v206
	v_pk_add_f32 v[100:101], v[100:101], v[240:241]
	v_lshlrev_b32_e32 v240, 16, v207
	v_and_b32_e32 v241, 0xffff0000, v207
	v_pk_add_f32 v[102:103], v[102:103], v[240:241]
	v_lshlrev_b32_e32 v240, 16, v208
	v_and_b32_e32 v241, 0xffff0000, v208
	v_pk_add_f32 v[96:97], v[96:97], v[240:241]
	v_lshlrev_b32_e32 v240, 16, v209
	v_and_b32_e32 v241, 0xffff0000, v209
	v_pk_add_f32 v[98:99], v[98:99], v[240:241]
	s_add_u32 s98, s62, 0x3c00
	s_addc_u32 s99, s63, 0
	global_load_dwordx4 v[206:209], v205, s[98:99]
	s_waitcnt vmcnt(8)
	v_lshlrev_b32_e32 v240, 16, v210
	v_and_b32_e32 v241, 0xffff0000, v210
	v_pk_add_f32 v[68:69], v[68:69], v[240:241]
	v_lshlrev_b32_e32 v240, 16, v211
	v_and_b32_e32 v241, 0xffff0000, v211
	v_pk_add_f32 v[70:71], v[70:71], v[240:241]
	v_lshlrev_b32_e32 v240, 16, v212
	v_and_b32_e32 v241, 0xffff0000, v212
	v_pk_add_f32 v[64:65], v[64:65], v[240:241]
	v_lshlrev_b32_e32 v240, 16, v213
	v_and_b32_e32 v241, 0xffff0000, v213
	v_pk_add_f32 v[66:67], v[66:67], v[240:241]
	s_add_u32 s42, s62, 0x20000
	s_addc_u32 s43, s63, 0
	global_load_dwordx4 v[210:213], v205, s[42:43]
	s_waitcnt vmcnt(8)
	v_lshlrev_b32_e32 v240, 16, v236
	v_and_b32_e32 v241, 0xffff0000, v236
	v_pk_add_f32 v[60:61], v[60:61], v[240:241]
	v_lshlrev_b32_e32 v240, 16, v237
	v_and_b32_e32 v241, 0xffff0000, v237
	v_pk_add_f32 v[62:63], v[62:63], v[240:241]
	v_lshlrev_b32_e32 v240, 16, v238
	v_and_b32_e32 v241, 0xffff0000, v238
	v_pk_add_f32 v[56:57], v[56:57], v[240:241]
	v_lshlrev_b32_e32 v240, 16, v239
	v_and_b32_e32 v241, 0xffff0000, v239
	v_pk_add_f32 v[58:59], v[58:59], v[240:241]
	s_add_u32 s98, s62, 0x21000
	s_addc_u32 s99, s63, 0
	global_load_dwordx4 v[236:239], v205, s[98:99]
	s_waitcnt vmcnt(8)
	v_lshlrev_b32_e32 v240, 16, v160
	v_and_b32_e32 v241, 0xffff0000, v160
	v_pk_add_f32 v[28:29], v[28:29], v[240:241]
	v_lshlrev_b32_e32 v240, 16, v161
	v_and_b32_e32 v241, 0xffff0000, v161
	v_pk_add_f32 v[30:31], v[30:31], v[240:241]
	v_lshlrev_b32_e32 v240, 16, v162
	v_and_b32_e32 v241, 0xffff0000, v162
	v_pk_add_f32 v[24:25], v[24:25], v[240:241]
	v_lshlrev_b32_e32 v240, 16, v163
	v_and_b32_e32 v241, 0xffff0000, v163
	v_pk_add_f32 v[26:27], v[26:27], v[240:241]
	s_add_u32 s42, s62, 0x20400
	s_addc_u32 s43, s63, 0
	global_load_dwordx4 v[160:163], v205, s[42:43]
	s_waitcnt vmcnt(8)
	v_lshlrev_b32_e32 v240, 16, v164
	v_and_b32_e32 v241, 0xffff0000, v164
	v_pk_add_f32 v[52:53], v[52:53], v[240:241]
	v_lshlrev_b32_e32 v240, 16, v165
	v_and_b32_e32 v241, 0xffff0000, v165
	v_pk_add_f32 v[54:55], v[54:55], v[240:241]
	v_lshlrev_b32_e32 v240, 16, v166
	v_and_b32_e32 v241, 0xffff0000, v166
	v_pk_add_f32 v[48:49], v[48:49], v[240:241]
	v_lshlrev_b32_e32 v240, 16, v167
	v_and_b32_e32 v241, 0xffff0000, v167
	v_pk_add_f32 v[50:51], v[50:51], v[240:241]
	s_add_u32 s98, s62, 0x21400
	s_addc_u32 s99, s63, 0
	global_load_dwordx4 v[164:167], v205, s[98:99]
	s_waitcnt vmcnt(8)
	v_lshlrev_b32_e32 v240, 16, v168
	v_and_b32_e32 v241, 0xffff0000, v168
	v_pk_add_f32 v[20:21], v[20:21], v[240:241]
	v_lshlrev_b32_e32 v240, 16, v169
	v_and_b32_e32 v241, 0xffff0000, v169
	v_pk_add_f32 v[22:23], v[22:23], v[240:241]
	v_lshlrev_b32_e32 v240, 16, v170
	v_and_b32_e32 v241, 0xffff0000, v170
	v_pk_add_f32 v[16:17], v[16:17], v[240:241]
	v_lshlrev_b32_e32 v240, 16, v171
	v_and_b32_e32 v241, 0xffff0000, v171
	v_pk_add_f32 v[18:19], v[18:19], v[240:241]
	s_add_u32 s42, s62, 0x20800
	s_addc_u32 s43, s63, 0
	global_load_dwordx4 v[168:171], v205, s[42:43]
	s_waitcnt vmcnt(8)
	v_lshlrev_b32_e32 v240, 16, v172
	v_and_b32_e32 v241, 0xffff0000, v172
	v_pk_add_f32 v[44:45], v[44:45], v[240:241]
	v_lshlrev_b32_e32 v240, 16, v173
	v_and_b32_e32 v241, 0xffff0000, v173
	v_pk_add_f32 v[46:47], v[46:47], v[240:241]
	v_lshlrev_b32_e32 v240, 16, v174
	v_and_b32_e32 v241, 0xffff0000, v174
	v_pk_add_f32 v[40:41], v[40:41], v[240:241]
	v_lshlrev_b32_e32 v240, 16, v175
	v_and_b32_e32 v241, 0xffff0000, v175
	v_pk_add_f32 v[42:43], v[42:43], v[240:241]
	s_add_u32 s98, s62, 0x21800
	s_addc_u32 s99, s63, 0
	global_load_dwordx4 v[172:175], v205, s[98:99]
	s_waitcnt vmcnt(8)
	v_lshlrev_b32_e32 v240, 16, v176
	v_and_b32_e32 v241, 0xffff0000, v176
	v_pk_add_f32 v[12:13], v[12:13], v[240:241]
	v_lshlrev_b32_e32 v240, 16, v177
	v_and_b32_e32 v241, 0xffff0000, v177
	v_pk_add_f32 v[14:15], v[14:15], v[240:241]
	v_lshlrev_b32_e32 v240, 16, v178
	v_and_b32_e32 v241, 0xffff0000, v178
	v_pk_add_f32 v[8:9], v[8:9], v[240:241]
	v_lshlrev_b32_e32 v240, 16, v179
	v_and_b32_e32 v241, 0xffff0000, v179
	v_pk_add_f32 v[10:11], v[10:11], v[240:241]
	s_add_u32 s42, s62, 0x20c00
	s_addc_u32 s43, s63, 0
	global_load_dwordx4 v[176:179], v205, s[42:43]
	s_waitcnt vmcnt(8)
	v_lshlrev_b32_e32 v240, 16, v180
	v_and_b32_e32 v241, 0xffff0000, v180
	v_pk_add_f32 v[36:37], v[36:37], v[240:241]
	v_lshlrev_b32_e32 v240, 16, v181
	v_and_b32_e32 v241, 0xffff0000, v181
	v_pk_add_f32 v[38:39], v[38:39], v[240:241]
	v_lshlrev_b32_e32 v240, 16, v182
	v_and_b32_e32 v241, 0xffff0000, v182
	v_pk_add_f32 v[32:33], v[32:33], v[240:241]
	v_lshlrev_b32_e32 v240, 16, v183
	v_and_b32_e32 v241, 0xffff0000, v183
	v_pk_add_f32 v[34:35], v[34:35], v[240:241]
	s_add_u32 s98, s62, 0x21c00
	s_addc_u32 s99, s63, 0
	global_load_dwordx4 v[180:183], v205, s[98:99]
	s_waitcnt vmcnt(8)
	v_lshlrev_b32_e32 v240, 16, v206
	v_and_b32_e32 v241, 0xffff0000, v206
	v_pk_add_f32 v[4:5], v[4:5], v[240:241]
	v_lshlrev_b32_e32 v240, 16, v207
	v_and_b32_e32 v241, 0xffff0000, v207
	v_pk_add_f32 v[6:7], v[6:7], v[240:241]
	v_lshlrev_b32_e32 v240, 16, v208
	v_and_b32_e32 v241, 0xffff0000, v208
	v_pk_add_f32 v[0:1], v[0:1], v[240:241]
	v_lshlrev_b32_e32 v240, 16, v209
	v_and_b32_e32 v241, 0xffff0000, v209
	v_pk_add_f32 v[2:3], v[2:3], v[240:241]
	s_add_u32 s42, s62, 0x22000
	s_addc_u32 s43, s63, 0
	global_load_dwordx4 v[206:209], v205, s[42:43]
	s_waitcnt vmcnt(8)
	v_lshlrev_b32_e32 v240, 16, v210
	v_and_b32_e32 v241, 0xffff0000, v210
	v_pk_add_f32 v[124:125], v[124:125], v[240:241]
	v_lshlrev_b32_e32 v240, 16, v211
	v_and_b32_e32 v241, 0xffff0000, v211
	v_pk_add_f32 v[126:127], v[126:127], v[240:241]
	v_lshlrev_b32_e32 v240, 16, v212
	v_and_b32_e32 v241, 0xffff0000, v212
	v_pk_add_f32 v[120:121], v[120:121], v[240:241]
	v_lshlrev_b32_e32 v240, 16, v213
	v_and_b32_e32 v241, 0xffff0000, v213
	v_pk_add_f32 v[122:123], v[122:123], v[240:241]
	s_add_u32 s98, s62, 0x23000
	s_addc_u32 s99, s63, 0
	global_load_dwordx4 v[210:213], v205, s[98:99]
	s_waitcnt vmcnt(8)
	v_lshlrev_b32_e32 v240, 16, v236
	v_and_b32_e32 v241, 0xffff0000, v236
	v_pk_add_f32 v[92:93], v[92:93], v[240:241]
	v_lshlrev_b32_e32 v240, 16, v237
	v_and_b32_e32 v241, 0xffff0000, v237
	v_pk_add_f32 v[94:95], v[94:95], v[240:241]
	v_lshlrev_b32_e32 v240, 16, v238
	v_and_b32_e32 v241, 0xffff0000, v238
	v_pk_add_f32 v[88:89], v[88:89], v[240:241]
	v_lshlrev_b32_e32 v240, 16, v239
	v_and_b32_e32 v241, 0xffff0000, v239
	v_pk_add_f32 v[90:91], v[90:91], v[240:241]
	s_add_u32 s42, s62, 0x22400
	s_addc_u32 s43, s63, 0
	global_load_dwordx4 v[236:239], v205, s[42:43]
	s_waitcnt vmcnt(8)
	v_lshlrev_b32_e32 v240, 16, v160
	v_and_b32_e32 v241, 0xffff0000, v160
	v_pk_add_f32 v[116:117], v[116:117], v[240:241]
	v_lshlrev_b32_e32 v240, 16, v161
	v_and_b32_e32 v241, 0xffff0000, v161
	v_pk_add_f32 v[118:119], v[118:119], v[240:241]
	v_lshlrev_b32_e32 v240, 16, v162
	v_and_b32_e32 v241, 0xffff0000, v162
	v_pk_add_f32 v[112:113], v[112:113], v[240:241]
	v_lshlrev_b32_e32 v240, 16, v163
	v_and_b32_e32 v241, 0xffff0000, v163
	v_pk_add_f32 v[114:115], v[114:115], v[240:241]
	s_add_u32 s98, s62, 0x23400
	s_addc_u32 s99, s63, 0
	global_load_dwordx4 v[160:163], v205, s[98:99]
	s_waitcnt vmcnt(8)
	v_lshlrev_b32_e32 v240, 16, v164
	v_and_b32_e32 v241, 0xffff0000, v164
	v_pk_add_f32 v[84:85], v[84:85], v[240:241]
	v_lshlrev_b32_e32 v240, 16, v165
	v_and_b32_e32 v241, 0xffff0000, v165
	v_pk_add_f32 v[86:87], v[86:87], v[240:241]
	v_lshlrev_b32_e32 v240, 16, v166
	v_and_b32_e32 v241, 0xffff0000, v166
	v_pk_add_f32 v[80:81], v[80:81], v[240:241]
	v_lshlrev_b32_e32 v240, 16, v167
	v_and_b32_e32 v241, 0xffff0000, v167
	v_pk_add_f32 v[82:83], v[82:83], v[240:241]
	s_add_u32 s42, s62, 0x22800
	s_addc_u32 s43, s63, 0
	global_load_dwordx4 v[164:167], v205, s[42:43]
	s_waitcnt vmcnt(8)
	v_lshlrev_b32_e32 v240, 16, v168
	v_and_b32_e32 v241, 0xffff0000, v168
	v_pk_add_f32 v[108:109], v[108:109], v[240:241]
	v_lshlrev_b32_e32 v240, 16, v169
	v_and_b32_e32 v241, 0xffff0000, v169
	v_pk_add_f32 v[110:111], v[110:111], v[240:241]
	v_lshlrev_b32_e32 v240, 16, v170
	v_and_b32_e32 v241, 0xffff0000, v170
	v_pk_add_f32 v[104:105], v[104:105], v[240:241]
	v_lshlrev_b32_e32 v240, 16, v171
	v_and_b32_e32 v241, 0xffff0000, v171
	v_pk_add_f32 v[106:107], v[106:107], v[240:241]
	s_add_u32 s98, s62, 0x23800
	s_addc_u32 s99, s63, 0
	global_load_dwordx4 v[168:171], v205, s[98:99]
	s_waitcnt vmcnt(8)
	v_lshlrev_b32_e32 v240, 16, v172
	v_and_b32_e32 v241, 0xffff0000, v172
	v_pk_add_f32 v[76:77], v[76:77], v[240:241]
	v_lshlrev_b32_e32 v240, 16, v173
	v_and_b32_e32 v241, 0xffff0000, v173
	v_pk_add_f32 v[78:79], v[78:79], v[240:241]
	v_lshlrev_b32_e32 v240, 16, v174
	v_and_b32_e32 v241, 0xffff0000, v174
	v_pk_add_f32 v[72:73], v[72:73], v[240:241]
	v_lshlrev_b32_e32 v240, 16, v175
	v_and_b32_e32 v241, 0xffff0000, v175
	v_pk_add_f32 v[74:75], v[74:75], v[240:241]
	s_add_u32 s42, s62, 0x22c00
	s_addc_u32 s43, s63, 0
	global_load_dwordx4 v[172:175], v205, s[42:43]
	s_waitcnt vmcnt(8)
	v_lshlrev_b32_e32 v240, 16, v176
	v_and_b32_e32 v241, 0xffff0000, v176
	v_pk_add_f32 v[100:101], v[100:101], v[240:241]
	v_lshlrev_b32_e32 v240, 16, v177
	v_and_b32_e32 v241, 0xffff0000, v177
	v_pk_add_f32 v[102:103], v[102:103], v[240:241]
	v_lshlrev_b32_e32 v240, 16, v178
	v_and_b32_e32 v241, 0xffff0000, v178
	v_pk_add_f32 v[96:97], v[96:97], v[240:241]
	v_lshlrev_b32_e32 v240, 16, v179
	v_and_b32_e32 v241, 0xffff0000, v179
	v_pk_add_f32 v[98:99], v[98:99], v[240:241]
	s_add_u32 s98, s62, 0x23c00
	s_addc_u32 s99, s63, 0
	global_load_dwordx4 v[176:179], v205, s[98:99]
	s_waitcnt vmcnt(8)
	v_lshlrev_b32_e32 v240, 16, v180
	v_and_b32_e32 v241, 0xffff0000, v180
	v_pk_add_f32 v[68:69], v[68:69], v[240:241]
	v_lshlrev_b32_e32 v240, 16, v181
	v_and_b32_e32 v241, 0xffff0000, v181
	v_pk_add_f32 v[70:71], v[70:71], v[240:241]
	v_lshlrev_b32_e32 v240, 16, v182
	v_and_b32_e32 v241, 0xffff0000, v182
	v_pk_add_f32 v[64:65], v[64:65], v[240:241]
	v_lshlrev_b32_e32 v240, 16, v183
	v_and_b32_e32 v241, 0xffff0000, v183
	v_pk_add_f32 v[66:67], v[66:67], v[240:241]
	s_add_u32 s42, s10, 0x0
	s_addc_u32 s43, s11, 0
	global_load_dwordx4 v[180:183], v203, s[42:43]
	s_waitcnt vmcnt(8)
	v_lshlrev_b32_e32 v240, 16, v206
	v_and_b32_e32 v241, 0xffff0000, v206
	v_pk_add_f32 v[60:61], v[60:61], v[240:241]
	v_lshlrev_b32_e32 v240, 16, v207
	v_and_b32_e32 v241, 0xffff0000, v207
	v_pk_add_f32 v[62:63], v[62:63], v[240:241]
	v_lshlrev_b32_e32 v240, 16, v208
	v_and_b32_e32 v241, 0xffff0000, v208
	v_pk_add_f32 v[56:57], v[56:57], v[240:241]
	v_lshlrev_b32_e32 v240, 16, v209
	v_and_b32_e32 v241, 0xffff0000, v209
	v_pk_add_f32 v[58:59], v[58:59], v[240:241]
	s_add_u32 s98, s10, 0x0
	s_addc_u32 s99, s11, 0
	global_load_dwordx4 v[206:209], v203, s[98:99] offset:16
	s_waitcnt vmcnt(8)
	v_lshlrev_b32_e32 v240, 16, v210
	v_and_b32_e32 v241, 0xffff0000, v210
	v_pk_add_f32 v[28:29], v[28:29], v[240:241]
	v_lshlrev_b32_e32 v240, 16, v211
	v_and_b32_e32 v241, 0xffff0000, v211
	v_pk_add_f32 v[30:31], v[30:31], v[240:241]
	v_lshlrev_b32_e32 v240, 16, v212
	v_and_b32_e32 v241, 0xffff0000, v212
	v_pk_add_f32 v[24:25], v[24:25], v[240:241]
	v_lshlrev_b32_e32 v240, 16, v213
	v_and_b32_e32 v241, 0xffff0000, v213
	v_pk_add_f32 v[26:27], v[26:27], v[240:241]
	s_add_u32 s42, s10, 0x200
	s_addc_u32 s43, s11, 0
	global_load_dwordx4 v[210:213], v203, s[42:43]
	s_waitcnt vmcnt(8)
	v_lshlrev_b32_e32 v240, 16, v236
	v_and_b32_e32 v241, 0xffff0000, v236
	v_pk_add_f32 v[52:53], v[52:53], v[240:241]
	v_lshlrev_b32_e32 v240, 16, v237
	v_and_b32_e32 v241, 0xffff0000, v237
	v_pk_add_f32 v[54:55], v[54:55], v[240:241]
	v_lshlrev_b32_e32 v240, 16, v238
	v_and_b32_e32 v241, 0xffff0000, v238
	v_pk_add_f32 v[48:49], v[48:49], v[240:241]
	v_lshlrev_b32_e32 v240, 16, v239
	v_and_b32_e32 v241, 0xffff0000, v239
	v_pk_add_f32 v[50:51], v[50:51], v[240:241]
	s_add_u32 s98, s10, 0x200
	s_addc_u32 s99, s11, 0
	global_load_dwordx4 v[236:239], v203, s[98:99] offset:16
	s_waitcnt vmcnt(8)
	v_lshlrev_b32_e32 v240, 16, v160
	v_and_b32_e32 v241, 0xffff0000, v160
	v_pk_add_f32 v[20:21], v[20:21], v[240:241]
	v_lshlrev_b32_e32 v240, 16, v161
	v_and_b32_e32 v241, 0xffff0000, v161
	v_pk_add_f32 v[22:23], v[22:23], v[240:241]
	v_lshlrev_b32_e32 v240, 16, v162
	v_and_b32_e32 v241, 0xffff0000, v162
	v_pk_add_f32 v[16:17], v[16:17], v[240:241]
	v_lshlrev_b32_e32 v240, 16, v163
	v_and_b32_e32 v241, 0xffff0000, v163
	v_pk_add_f32 v[18:19], v[18:19], v[240:241]
	s_add_u32 s42, s10, 0x10000
	s_addc_u32 s43, s11, 0
	global_load_dwordx4 v[160:163], v203, s[42:43]
	s_waitcnt vmcnt(8)
	v_lshlrev_b32_e32 v240, 16, v164
	v_and_b32_e32 v241, 0xffff0000, v164
	v_pk_add_f32 v[44:45], v[44:45], v[240:241]
	v_lshlrev_b32_e32 v240, 16, v165
	v_and_b32_e32 v241, 0xffff0000, v165
	v_pk_add_f32 v[46:47], v[46:47], v[240:241]
	v_lshlrev_b32_e32 v240, 16, v166
	v_and_b32_e32 v241, 0xffff0000, v166
	v_pk_add_f32 v[40:41], v[40:41], v[240:241]
	v_lshlrev_b32_e32 v240, 16, v167
	v_and_b32_e32 v241, 0xffff0000, v167
	v_pk_add_f32 v[42:43], v[42:43], v[240:241]
	s_add_u32 s98, s10, 0x10000
	s_addc_u32 s99, s11, 0
	global_load_dwordx4 v[164:167], v203, s[98:99] offset:16
	s_waitcnt vmcnt(8)
	v_lshlrev_b32_e32 v240, 16, v168
	v_and_b32_e32 v241, 0xffff0000, v168
	v_pk_add_f32 v[12:13], v[12:13], v[240:241]
	v_lshlrev_b32_e32 v240, 16, v169
	v_and_b32_e32 v241, 0xffff0000, v169
	v_pk_add_f32 v[14:15], v[14:15], v[240:241]
	v_lshlrev_b32_e32 v240, 16, v170
	v_and_b32_e32 v241, 0xffff0000, v170
	v_pk_add_f32 v[8:9], v[8:9], v[240:241]
	v_lshlrev_b32_e32 v240, 16, v171
	v_and_b32_e32 v241, 0xffff0000, v171
	v_pk_add_f32 v[10:11], v[10:11], v[240:241]
	s_add_u32 s42, s10, 0x10200
	s_addc_u32 s43, s11, 0
	global_load_dwordx4 v[168:171], v203, s[42:43]
	s_waitcnt vmcnt(8)
	v_lshlrev_b32_e32 v240, 16, v172
	v_and_b32_e32 v241, 0xffff0000, v172
	v_pk_add_f32 v[36:37], v[36:37], v[240:241]
	v_lshlrev_b32_e32 v240, 16, v173
	v_and_b32_e32 v241, 0xffff0000, v173
	v_pk_add_f32 v[38:39], v[38:39], v[240:241]
	v_lshlrev_b32_e32 v240, 16, v174
	v_and_b32_e32 v241, 0xffff0000, v174
	v_pk_add_f32 v[32:33], v[32:33], v[240:241]
	v_lshlrev_b32_e32 v240, 16, v175
	v_and_b32_e32 v241, 0xffff0000, v175
	v_pk_add_f32 v[34:35], v[34:35], v[240:241]
	s_add_u32 s98, s10, 0x10200
	s_addc_u32 s99, s11, 0
	global_load_dwordx4 v[172:175], v203, s[98:99] offset:16
	s_waitcnt vmcnt(8)
	v_lshlrev_b32_e32 v240, 16, v176
	v_and_b32_e32 v241, 0xffff0000, v176
	v_pk_add_f32 v[4:5], v[4:5], v[240:241]
	v_lshlrev_b32_e32 v240, 16, v177
	v_and_b32_e32 v241, 0xffff0000, v177
	v_pk_add_f32 v[6:7], v[6:7], v[240:241]
	v_lshlrev_b32_e32 v240, 16, v178
	v_and_b32_e32 v241, 0xffff0000, v178
	v_pk_add_f32 v[0:1], v[0:1], v[240:241]
	v_lshlrev_b32_e32 v240, 16, v179
	v_and_b32_e32 v241, 0xffff0000, v179
	v_pk_add_f32 v[2:3], v[2:3], v[240:241]
	s_add_u32 s42, s10, 0x20000
	s_addc_u32 s43, s11, 0
	global_load_dwordx4 v[176:179], v203, s[42:43]
	s_waitcnt vmcnt(8)
	v_pk_fma_f32 v[124:125], v[148:149], v[124:125], v[180:181]
	v_pk_fma_f32 v[126:127], v[150:151], v[126:127], v[182:183]
	s_add_u32 s98, s10, 0x0
	s_addc_u32 s99, s11, 0
	global_store_dwordx4 v203, v[124:127], s[98:99]
	s_add_u32 s42, s10, 0x20000
	s_addc_u32 s43, s11, 0
	global_load_dwordx4 v[180:183], v203, s[42:43] offset:16
	s_waitcnt vmcnt(9)
	v_pk_fma_f32 v[120:121], v[144:145], v[120:121], v[206:207]
	v_pk_fma_f32 v[122:123], v[146:147], v[122:123], v[208:209]
	s_add_u32 s98, s10, 0x0
	s_addc_u32 s99, s11, 0
	global_store_dwordx4 v203, v[120:123], s[98:99] offset:16
	s_add_u32 s42, s10, 0x20200
	s_addc_u32 s43, s11, 0
	global_load_dwordx4 v[206:209], v203, s[42:43]
	s_waitcnt vmcnt(10)
	v_pk_fma_f32 v[92:93], v[156:157], v[92:93], v[210:211]
	v_pk_fma_f32 v[94:95], v[158:159], v[94:95], v[212:213]
	s_add_u32 s98, s10, 0x200
	s_addc_u32 s99, s11, 0
	global_store_dwordx4 v203, v[92:95], s[98:99]
	s_add_u32 s42, s10, 0x20200
	s_addc_u32 s43, s11, 0
	global_load_dwordx4 v[210:213], v203, s[42:43] offset:16
	s_waitcnt vmcnt(11)
	v_pk_fma_f32 v[88:89], v[152:153], v[88:89], v[236:237]
	v_pk_fma_f32 v[90:91], v[154:155], v[90:91], v[238:239]
	s_add_u32 s98, s10, 0x200
	s_addc_u32 s99, s11, 0
	global_store_dwordx4 v203, v[88:91], s[98:99] offset:16
	s_add_u32 s42, s10, 0x30000
	s_addc_u32 s43, s11, 0
	global_load_dwordx4 v[236:239], v203, s[42:43]
	s_waitcnt vmcnt(12)
	v_pk_fma_f32 v[116:117], v[148:149], v[116:117], v[160:161]
	v_pk_fma_f32 v[118:119], v[150:151], v[118:119], v[162:163]
	s_add_u32 s98, s10, 0x10000
	s_addc_u32 s99, s11, 0
	global_store_dwordx4 v203, v[116:119], s[98:99]
	s_add_u32 s42, s10, 0x30000
	s_addc_u32 s43, s11, 0
	global_load_dwordx4 v[160:163], v203, s[42:43] offset:16
	s_waitcnt vmcnt(13)
	v_pk_fma_f32 v[112:113], v[144:145], v[112:113], v[164:165]
	v_pk_fma_f32 v[114:115], v[146:147], v[114:115], v[166:167]
	s_add_u32 s98, s10, 0x10000
	s_addc_u32 s99, s11, 0
	global_store_dwordx4 v203, v[112:115], s[98:99] offset:16
	s_add_u32 s42, s10, 0x30200
	s_addc_u32 s43, s11, 0
	global_load_dwordx4 v[164:167], v203, s[42:43]
	s_waitcnt vmcnt(14)
	v_pk_fma_f32 v[84:85], v[156:157], v[84:85], v[168:169]
	v_pk_fma_f32 v[86:87], v[158:159], v[86:87], v[170:171]
	s_add_u32 s98, s10, 0x10200
	s_addc_u32 s99, s11, 0
	global_store_dwordx4 v203, v[84:87], s[98:99]
	s_add_u32 s42, s10, 0x30200
	s_addc_u32 s43, s11, 0
	global_load_dwordx4 v[168:171], v203, s[42:43] offset:16
	s_waitcnt vmcnt(15)
	v_pk_fma_f32 v[80:81], v[152:153], v[80:81], v[172:173]
	v_pk_fma_f32 v[82:83], v[154:155], v[82:83], v[174:175]
	s_add_u32 s98, s10, 0x10200
	s_addc_u32 s99, s11, 0
	global_store_dwordx4 v203, v[80:83], s[98:99] offset:16
	s_add_u32 s42, s10, 0x80000
	s_addc_u32 s43, s11, 0
	global_load_dwordx4 v[172:175], v203, s[42:43]
	s_waitcnt vmcnt(16)
	v_pk_fma_f32 v[108:109], v[148:149], v[108:109], v[176:177]
	v_pk_fma_f32 v[110:111], v[150:151], v[110:111], v[178:179]
	s_add_u32 s98, s10, 0x20000
	s_addc_u32 s99, s11, 0
	global_store_dwordx4 v203, v[108:111], s[98:99]
	s_add_u32 s42, s10, 0x80000
	s_addc_u32 s43, s11, 0
	global_load_dwordx4 v[176:179], v203, s[42:43] offset:16
	s_waitcnt vmcnt(16)
	v_pk_fma_f32 v[104:105], v[144:145], v[104:105], v[180:181]
	v_pk_fma_f32 v[106:107], v[146:147], v[106:107], v[182:183]
	s_add_u32 s98, s10, 0x20000
	s_addc_u32 s99, s11, 0
	global_store_dwordx4 v203, v[104:107], s[98:99] offset:16
	s_add_u32 s42, s10, 0x80200
	s_addc_u32 s43, s11, 0
	global_load_dwordx4 v[180:183], v203, s[42:43]
	s_waitcnt vmcnt(16)
	v_pk_fma_f32 v[76:77], v[156:157], v[76:77], v[206:207]
	v_pk_fma_f32 v[78:79], v[158:159], v[78:79], v[208:209]
	s_add_u32 s98, s10, 0x20200
	s_addc_u32 s99, s11, 0
	global_store_dwordx4 v203, v[76:79], s[98:99]
	s_add_u32 s42, s10, 0x80200
	s_addc_u32 s43, s11, 0
	global_load_dwordx4 v[206:209], v203, s[42:43] offset:16
	s_waitcnt vmcnt(16)
	v_pk_fma_f32 v[72:73], v[152:153], v[72:73], v[210:211]
	v_pk_fma_f32 v[74:75], v[154:155], v[74:75], v[212:213]
	s_add_u32 s98, s10, 0x20200
	s_addc_u32 s99, s11, 0
	global_store_dwordx4 v203, v[72:75], s[98:99] offset:16
	s_add_u32 s42, s10, 0x90000
	s_addc_u32 s43, s11, 0
	global_load_dwordx4 v[210:213], v203, s[42:43]
	s_waitcnt vmcnt(16)
	v_pk_fma_f32 v[100:101], v[148:149], v[100:101], v[236:237]
	v_pk_fma_f32 v[102:103], v[150:151], v[102:103], v[238:239]
	s_add_u32 s98, s10, 0x30000
	s_addc_u32 s99, s11, 0
	global_store_dwordx4 v203, v[100:103], s[98:99]
	s_add_u32 s42, s10, 0x90000
	s_addc_u32 s43, s11, 0
	global_load_dwordx4 v[236:239], v203, s[42:43] offset:16
	s_waitcnt vmcnt(16)
	v_pk_fma_f32 v[96:97], v[144:145], v[96:97], v[160:161]
	v_pk_fma_f32 v[98:99], v[146:147], v[98:99], v[162:163]
	s_add_u32 s98, s10, 0x30000
	s_addc_u32 s99, s11, 0
	global_store_dwordx4 v203, v[96:99], s[98:99] offset:16
	s_add_u32 s42, s10, 0x90200
	s_addc_u32 s43, s11, 0
	global_load_dwordx4 v[160:163], v203, s[42:43]
	s_waitcnt vmcnt(16)
	v_pk_fma_f32 v[68:69], v[156:157], v[68:69], v[164:165]
	v_pk_fma_f32 v[70:71], v[158:159], v[70:71], v[166:167]
	s_add_u32 s98, s10, 0x30200
	s_addc_u32 s99, s11, 0
	global_store_dwordx4 v203, v[68:71], s[98:99]
	s_add_u32 s42, s10, 0x90200
	s_addc_u32 s43, s11, 0
	global_load_dwordx4 v[164:167], v203, s[42:43] offset:16
	s_waitcnt vmcnt(16)
	v_pk_fma_f32 v[64:65], v[152:153], v[64:65], v[168:169]
	v_pk_fma_f32 v[66:67], v[154:155], v[66:67], v[170:171]
	s_add_u32 s98, s10, 0x30200
	s_addc_u32 s99, s11, 0
	global_store_dwordx4 v203, v[64:67], s[98:99] offset:16
	s_add_u32 s42, s10, 0xa0000
	s_addc_u32 s43, s11, 0
	global_load_dwordx4 v[168:171], v203, s[42:43]
	s_waitcnt vmcnt(16)
	v_pk_fma_f32 v[60:61], v[148:149], v[60:61], v[172:173]
	v_pk_fma_f32 v[62:63], v[150:151], v[62:63], v[174:175]
	s_add_u32 s98, s10, 0x80000
	s_addc_u32 s99, s11, 0
	global_store_dwordx4 v203, v[60:63], s[98:99]
	s_add_u32 s42, s10, 0xa0000
	s_addc_u32 s43, s11, 0
	global_load_dwordx4 v[172:175], v203, s[42:43] offset:16
	s_waitcnt vmcnt(16)
	v_pk_fma_f32 v[56:57], v[144:145], v[56:57], v[176:177]
	v_pk_fma_f32 v[58:59], v[146:147], v[58:59], v[178:179]
	s_add_u32 s98, s10, 0x80000
	s_addc_u32 s99, s11, 0
	global_store_dwordx4 v203, v[56:59], s[98:99] offset:16
	s_add_u32 s42, s10, 0xa0200
	s_addc_u32 s43, s11, 0
	global_load_dwordx4 v[176:179], v203, s[42:43]
	s_waitcnt vmcnt(16)
	v_pk_fma_f32 v[28:29], v[156:157], v[28:29], v[180:181]
	v_pk_fma_f32 v[30:31], v[158:159], v[30:31], v[182:183]
	s_add_u32 s98, s10, 0x80200
	s_addc_u32 s99, s11, 0
	global_store_dwordx4 v203, v[28:31], s[98:99]
	s_add_u32 s42, s10, 0xa0200
	s_addc_u32 s43, s11, 0
	global_load_dwordx4 v[180:183], v203, s[42:43] offset:16
	s_waitcnt vmcnt(16)
	v_pk_fma_f32 v[24:25], v[152:153], v[24:25], v[206:207]
	v_pk_fma_f32 v[26:27], v[154:155], v[26:27], v[208:209]
	s_add_u32 s98, s10, 0x80200
	s_addc_u32 s99, s11, 0
	global_store_dwordx4 v203, v[24:27], s[98:99] offset:16
	s_waitcnt vmcnt(15)
	v_pk_fma_f32 v[52:53], v[148:149], v[52:53], v[210:211]
	v_pk_fma_f32 v[54:55], v[150:151], v[54:55], v[212:213]
	s_add_u32 s42, s10, 0x90000
	s_addc_u32 s43, s11, 0
	global_store_dwordx4 v203, v[52:55], s[42:43]
	s_waitcnt vmcnt(14)
	v_pk_fma_f32 v[48:49], v[144:145], v[48:49], v[236:237]
	v_pk_fma_f32 v[50:51], v[146:147], v[50:51], v[238:239]
	s_add_u32 s98, s10, 0x90000
	s_addc_u32 s99, s11, 0
	global_store_dwordx4 v203, v[48:51], s[98:99] offset:16
	s_waitcnt vmcnt(13)
	v_pk_fma_f32 v[20:21], v[156:157], v[20:21], v[160:161]
	v_pk_fma_f32 v[22:23], v[158:159], v[22:23], v[162:163]
	s_add_u32 s42, s10, 0x90200
	s_addc_u32 s43, s11, 0
	global_store_dwordx4 v203, v[20:23], s[42:43]
	s_waitcnt vmcnt(12)
	v_pk_fma_f32 v[16:17], v[152:153], v[16:17], v[164:165]
	v_pk_fma_f32 v[18:19], v[154:155], v[18:19], v[166:167]
	s_add_u32 s98, s10, 0x90200
	s_addc_u32 s99, s11, 0
	global_store_dwordx4 v203, v[16:19], s[98:99] offset:16
	s_waitcnt vmcnt(11)
	v_pk_fma_f32 v[44:45], v[148:149], v[44:45], v[168:169]
	v_pk_fma_f32 v[46:47], v[150:151], v[46:47], v[170:171]
	s_add_u32 s42, s10, 0xa0000
	s_addc_u32 s43, s11, 0
	global_store_dwordx4 v203, v[44:47], s[42:43]
	s_waitcnt vmcnt(10)
	v_pk_fma_f32 v[40:41], v[144:145], v[40:41], v[172:173]
	v_pk_fma_f32 v[42:43], v[146:147], v[42:43], v[174:175]
	s_add_u32 s98, s10, 0xa0000
	s_addc_u32 s99, s11, 0
	global_store_dwordx4 v203, v[40:43], s[98:99] offset:16
	s_waitcnt vmcnt(9)
	v_pk_fma_f32 v[12:13], v[156:157], v[12:13], v[176:177]
	v_pk_fma_f32 v[14:15], v[158:159], v[14:15], v[178:179]
	s_add_u32 s42, s10, 0xa0200
	s_addc_u32 s43, s11, 0
	global_store_dwordx4 v203, v[12:15], s[42:43]
	s_waitcnt vmcnt(8)
	v_pk_fma_f32 v[8:9], v[152:153], v[8:9], v[180:181]
	v_pk_fma_f32 v[10:11], v[154:155], v[10:11], v[182:183]
	s_add_u32 s98, s10, 0xa0200
	s_addc_u32 s99, s11, 0
	global_store_dwordx4 v203, v[8:11], s[98:99] offset:16
	s_branch .Lfq_predone
.Lfq_np1:
	s_add_u32 s42, s62, 0x0
	s_addc_u32 s43, s63, 0
	global_load_dwordx4 v[160:163], v205, s[42:43]
	s_add_u32 s98, s62, 0x1000
	s_addc_u32 s99, s63, 0
	global_load_dwordx4 v[164:167], v205, s[98:99]
	s_add_u32 s42, s62, 0x400
	s_addc_u32 s43, s63, 0
	global_load_dwordx4 v[168:171], v205, s[42:43]
	s_add_u32 s98, s62, 0x1400
	s_addc_u32 s99, s63, 0
	global_load_dwordx4 v[172:175], v205, s[98:99]
	s_add_u32 s42, s62, 0x800
	s_addc_u32 s43, s63, 0
	global_load_dwordx4 v[176:179], v205, s[42:43]
	s_add_u32 s98, s62, 0x1800
	s_addc_u32 s99, s63, 0
	global_load_dwordx4 v[180:183], v205, s[98:99]
	s_add_u32 s42, s62, 0xc00
	s_addc_u32 s43, s63, 0
	global_load_dwordx4 v[206:209], v205, s[42:43]
	s_add_u32 s98, s62, 0x1c00
	s_addc_u32 s99, s63, 0
	global_load_dwordx4 v[210:213], v205, s[98:99]
	s_add_u32 s42, s62, 0x2000
	s_addc_u32 s43, s63, 0
	global_load_dwordx4 v[236:239], v205, s[42:43]
	s_waitcnt vmcnt(8)
	v_lshlrev_b32_e32 v240, 16, v160
	v_and_b32_e32 v241, 0xffff0000, v160
	v_pk_add_f32 v[124:125], v[124:125], v[240:241]
	v_lshlrev_b32_e32 v240, 16, v161
	v_and_b32_e32 v241, 0xffff0000, v161
	v_pk_add_f32 v[126:127], v[126:127], v[240:241]
	v_lshlrev_b32_e32 v240, 16, v162
	v_and_b32_e32 v241, 0xffff0000, v162
	v_pk_add_f32 v[120:121], v[120:121], v[240:241]
	v_lshlrev_b32_e32 v240, 16, v163
	v_and_b32_e32 v241, 0xffff0000, v163
	v_pk_add_f32 v[122:123], v[122:123], v[240:241]
	s_add_u32 s98, s62, 0x3000
	s_addc_u32 s99, s63, 0
	global_load_dwordx4 v[160:163], v205, s[98:99]
	s_waitcnt vmcnt(8)
	v_lshlrev_b32_e32 v240, 16, v164
	v_and_b32_e32 v241, 0xffff0000, v164
	v_pk_add_f32 v[92:93], v[92:93], v[240:241]
	v_lshlrev_b32_e32 v240, 16, v165
	v_and_b32_e32 v241, 0xffff0000, v165
	v_pk_add_f32 v[94:95], v[94:95], v[240:241]
	v_lshlrev_b32_e32 v240, 16, v166
	v_and_b32_e32 v241, 0xffff0000, v166
	v_pk_add_f32 v[88:89], v[88:89], v[240:241]
	v_lshlrev_b32_e32 v240, 16, v167
	v_and_b32_e32 v241, 0xffff0000, v167
	v_pk_add_f32 v[90:91], v[90:91], v[240:241]
	s_add_u32 s42, s62, 0x2400
	s_addc_u32 s43, s63, 0
	global_load_dwordx4 v[164:167], v205, s[42:43]
	s_waitcnt vmcnt(8)
	v_lshlrev_b32_e32 v240, 16, v168
	v_and_b32_e32 v241, 0xffff0000, v168
	v_pk_add_f32 v[116:117], v[116:117], v[240:241]
	v_lshlrev_b32_e32 v240, 16, v169
	v_and_b32_e32 v241, 0xffff0000, v169
	v_pk_add_f32 v[118:119], v[118:119], v[240:241]
	v_lshlrev_b32_e32 v240, 16, v170
	v_and_b32_e32 v241, 0xffff0000, v170
	v_pk_add_f32 v[112:113], v[112:113], v[240:241]
	v_lshlrev_b32_e32 v240, 16, v171
	v_and_b32_e32 v241, 0xffff0000, v171
	v_pk_add_f32 v[114:115], v[114:115], v[240:241]
	s_add_u32 s98, s62, 0x3400
	s_addc_u32 s99, s63, 0
	global_load_dwordx4 v[168:171], v205, s[98:99]
	s_waitcnt vmcnt(8)
	v_lshlrev_b32_e32 v240, 16, v172
	v_and_b32_e32 v241, 0xffff0000, v172
	v_pk_add_f32 v[84:85], v[84:85], v[240:241]
	v_lshlrev_b32_e32 v240, 16, v173
	v_and_b32_e32 v241, 0xffff0000, v173
	v_pk_add_f32 v[86:87], v[86:87], v[240:241]
	v_lshlrev_b32_e32 v240, 16, v174
	v_and_b32_e32 v241, 0xffff0000, v174
	v_pk_add_f32 v[80:81], v[80:81], v[240:241]
	v_lshlrev_b32_e32 v240, 16, v175
	v_and_b32_e32 v241, 0xffff0000, v175
	v_pk_add_f32 v[82:83], v[82:83], v[240:241]
	s_add_u32 s42, s62, 0x2800
	s_addc_u32 s43, s63, 0
	global_load_dwordx4 v[172:175], v205, s[42:43]
	s_waitcnt vmcnt(8)
	v_lshlrev_b32_e32 v240, 16, v176
	v_and_b32_e32 v241, 0xffff0000, v176
	v_pk_add_f32 v[108:109], v[108:109], v[240:241]
	v_lshlrev_b32_e32 v240, 16, v177
	v_and_b32_e32 v241, 0xffff0000, v177
	v_pk_add_f32 v[110:111], v[110:111], v[240:241]
	v_lshlrev_b32_e32 v240, 16, v178
	v_and_b32_e32 v241, 0xffff0000, v178
	v_pk_add_f32 v[104:105], v[104:105], v[240:241]
	v_lshlrev_b32_e32 v240, 16, v179
	v_and_b32_e32 v241, 0xffff0000, v179
	v_pk_add_f32 v[106:107], v[106:107], v[240:241]
	s_add_u32 s98, s62, 0x3800
	s_addc_u32 s99, s63, 0
	global_load_dwordx4 v[176:179], v205, s[98:99]
	s_waitcnt vmcnt(8)
	v_lshlrev_b32_e32 v240, 16, v180
	v_and_b32_e32 v241, 0xffff0000, v180
	v_pk_add_f32 v[76:77], v[76:77], v[240:241]
	v_lshlrev_b32_e32 v240, 16, v181
	v_and_b32_e32 v241, 0xffff0000, v181
	v_pk_add_f32 v[78:79], v[78:79], v[240:241]
	v_lshlrev_b32_e32 v240, 16, v182
	v_and_b32_e32 v241, 0xffff0000, v182
	v_pk_add_f32 v[72:73], v[72:73], v[240:241]
	v_lshlrev_b32_e32 v240, 16, v183
	v_and_b32_e32 v241, 0xffff0000, v183
	v_pk_add_f32 v[74:75], v[74:75], v[240:241]
	s_add_u32 s42, s62, 0x2c00
	s_addc_u32 s43, s63, 0
	global_load_dwordx4 v[180:183], v205, s[42:43]
	s_waitcnt vmcnt(8)
	v_lshlrev_b32_e32 v240, 16, v206
	v_and_b32_e32 v241, 0xffff0000, v206
	v_pk_add_f32 v[100:101], v[100:101], v[240:241]
	v_lshlrev_b32_e32 v240, 16, v207
	v_and_b32_e32 v241, 0xffff0000, v207
	v_pk_add_f32 v[102:103], v[102:103], v[240:241]
	v_lshlrev_b32_e32 v240, 16, v208
	v_and_b32_e32 v241, 0xffff0000, v208
	v_pk_add_f32 v[96:97], v[96:97], v[240:241]
	v_lshlrev_b32_e32 v240, 16, v209
	v_and_b32_e32 v241, 0xffff0000, v209
	v_pk_add_f32 v[98:99], v[98:99], v[240:241]
	s_add_u32 s98, s62, 0x3c00
	s_addc_u32 s99, s63, 0
	global_load_dwordx4 v[206:209], v205, s[98:99]
	s_waitcnt vmcnt(8)
	v_lshlrev_b32_e32 v240, 16, v210
	v_and_b32_e32 v241, 0xffff0000, v210
	v_pk_add_f32 v[68:69], v[68:69], v[240:241]
	v_lshlrev_b32_e32 v240, 16, v211
	v_and_b32_e32 v241, 0xffff0000, v211
	v_pk_add_f32 v[70:71], v[70:71], v[240:241]
	v_lshlrev_b32_e32 v240, 16, v212
	v_and_b32_e32 v241, 0xffff0000, v212
	v_pk_add_f32 v[64:65], v[64:65], v[240:241]
	v_lshlrev_b32_e32 v240, 16, v213
	v_and_b32_e32 v241, 0xffff0000, v213
	v_pk_add_f32 v[66:67], v[66:67], v[240:241]
	s_add_u32 s42, s10, 0x0
	s_addc_u32 s43, s11, 0
	global_load_dwordx4 v[210:213], v203, s[42:43]
	s_waitcnt vmcnt(8)
	v_lshlrev_b32_e32 v240, 16, v236
	v_and_b32_e32 v241, 0xffff0000, v236
	v_pk_add_f32 v[60:61], v[60:61], v[240:241]
	v_lshlrev_b32_e32 v240, 16, v237
	v_and_b32_e32 v241, 0xffff0000, v237
	v_pk_add_f32 v[62:63], v[62:63], v[240:241]
	v_lshlrev_b32_e32 v240, 16, v238
	v_and_b32_e32 v241, 0xffff0000, v238
	v_pk_add_f32 v[56:57], v[56:57], v[240:241]
	v_lshlrev_b32_e32 v240, 16, v239
	v_and_b32_e32 v241, 0xffff0000, v239
	v_pk_add_f32 v[58:59], v[58:59], v[240:241]
	s_add_u32 s98, s10, 0x0
	s_addc_u32 s99, s11, 0
	global_load_dwordx4 v[236:239], v203, s[98:99] offset:16
	s_waitcnt vmcnt(8)
	v_lshlrev_b32_e32 v240, 16, v160
	v_and_b32_e32 v241, 0xffff0000, v160
	v_pk_add_f32 v[28:29], v[28:29], v[240:241]
	v_lshlrev_b32_e32 v240, 16, v161
	v_and_b32_e32 v241, 0xffff0000, v161
	v_pk_add_f32 v[30:31], v[30:31], v[240:241]
	v_lshlrev_b32_e32 v240, 16, v162
	v_and_b32_e32 v241, 0xffff0000, v162
	v_pk_add_f32 v[24:25], v[24:25], v[240:241]
	v_lshlrev_b32_e32 v240, 16, v163
	v_and_b32_e32 v241, 0xffff0000, v163
	v_pk_add_f32 v[26:27], v[26:27], v[240:241]
	s_add_u32 s42, s10, 0x200
	s_addc_u32 s43, s11, 0
	global_load_dwordx4 v[160:163], v203, s[42:43]
	s_waitcnt vmcnt(8)
	v_lshlrev_b32_e32 v240, 16, v164
	v_and_b32_e32 v241, 0xffff0000, v164
	v_pk_add_f32 v[52:53], v[52:53], v[240:241]
	v_lshlrev_b32_e32 v240, 16, v165
	v_and_b32_e32 v241, 0xffff0000, v165
	v_pk_add_f32 v[54:55], v[54:55], v[240:241]
	v_lshlrev_b32_e32 v240, 16, v166
	v_and_b32_e32 v241, 0xffff0000, v166
	v_pk_add_f32 v[48:49], v[48:49], v[240:241]
	v_lshlrev_b32_e32 v240, 16, v167
	v_and_b32_e32 v241, 0xffff0000, v167
	v_pk_add_f32 v[50:51], v[50:51], v[240:241]
	s_add_u32 s98, s10, 0x200
	s_addc_u32 s99, s11, 0
	global_load_dwordx4 v[164:167], v203, s[98:99] offset:16
	s_waitcnt vmcnt(8)
	v_lshlrev_b32_e32 v240, 16, v168
	v_and_b32_e32 v241, 0xffff0000, v168
	v_pk_add_f32 v[20:21], v[20:21], v[240:241]
	v_lshlrev_b32_e32 v240, 16, v169
	v_and_b32_e32 v241, 0xffff0000, v169
	v_pk_add_f32 v[22:23], v[22:23], v[240:241]
	v_lshlrev_b32_e32 v240, 16, v170
	v_and_b32_e32 v241, 0xffff0000, v170
	v_pk_add_f32 v[16:17], v[16:17], v[240:241]
	v_lshlrev_b32_e32 v240, 16, v171
	v_and_b32_e32 v241, 0xffff0000, v171
	v_pk_add_f32 v[18:19], v[18:19], v[240:241]
	s_add_u32 s42, s10, 0x10000
	s_addc_u32 s43, s11, 0
	global_load_dwordx4 v[168:171], v203, s[42:43]
	s_waitcnt vmcnt(8)
	v_lshlrev_b32_e32 v240, 16, v172
	v_and_b32_e32 v241, 0xffff0000, v172
	v_pk_add_f32 v[44:45], v[44:45], v[240:241]
	v_lshlrev_b32_e32 v240, 16, v173
	v_and_b32_e32 v241, 0xffff0000, v173
	v_pk_add_f32 v[46:47], v[46:47], v[240:241]
	v_lshlrev_b32_e32 v240, 16, v174
	v_and_b32_e32 v241, 0xffff0000, v174
	v_pk_add_f32 v[40:41], v[40:41], v[240:241]
	v_lshlrev_b32_e32 v240, 16, v175
	v_and_b32_e32 v241, 0xffff0000, v175
	v_pk_add_f32 v[42:43], v[42:43], v[240:241]
	s_add_u32 s98, s10, 0x10000
	s_addc_u32 s99, s11, 0
	global_load_dwordx4 v[172:175], v203, s[98:99] offset:16
	s_waitcnt vmcnt(8)
	v_lshlrev_b32_e32 v240, 16, v176
	v_and_b32_e32 v241, 0xffff0000, v176
	v_pk_add_f32 v[12:13], v[12:13], v[240:241]
	v_lshlrev_b32_e32 v240, 16, v177
	v_and_b32_e32 v241, 0xffff0000, v177
	v_pk_add_f32 v[14:15], v[14:15], v[240:241]
	v_lshlrev_b32_e32 v240, 16, v178
	v_and_b32_e32 v241, 0xffff0000, v178
	v_pk_add_f32 v[8:9], v[8:9], v[240:241]
	v_lshlrev_b32_e32 v240, 16, v179
	v_and_b32_e32 v241, 0xffff0000, v179
	v_pk_add_f32 v[10:11], v[10:11], v[240:241]
	s_add_u32 s42, s10, 0x10200
	s_addc_u32 s43, s11, 0
	global_load_dwordx4 v[176:179], v203, s[42:43]
	s_waitcnt vmcnt(8)
	v_lshlrev_b32_e32 v240, 16, v180
	v_and_b32_e32 v241, 0xffff0000, v180
	v_pk_add_f32 v[36:37], v[36:37], v[240:241]
	v_lshlrev_b32_e32 v240, 16, v181
	v_and_b32_e32 v241, 0xffff0000, v181
	v_pk_add_f32 v[38:39], v[38:39], v[240:241]
	v_lshlrev_b32_e32 v240, 16, v182
	v_and_b32_e32 v241, 0xffff0000, v182
	v_pk_add_f32 v[32:33], v[32:33], v[240:241]
	v_lshlrev_b32_e32 v240, 16, v183
	v_and_b32_e32 v241, 0xffff0000, v183
	v_pk_add_f32 v[34:35], v[34:35], v[240:241]
	s_add_u32 s98, s10, 0x10200
	s_addc_u32 s99, s11, 0
	global_load_dwordx4 v[180:183], v203, s[98:99] offset:16
	s_waitcnt vmcnt(8)
	v_lshlrev_b32_e32 v240, 16, v206
	v_and_b32_e32 v241, 0xffff0000, v206
	v_pk_add_f32 v[4:5], v[4:5], v[240:241]
	v_lshlrev_b32_e32 v240, 16, v207
	v_and_b32_e32 v241, 0xffff0000, v207
	v_pk_add_f32 v[6:7], v[6:7], v[240:241]
	v_lshlrev_b32_e32 v240, 16, v208
	v_and_b32_e32 v241, 0xffff0000, v208
	v_pk_add_f32 v[0:1], v[0:1], v[240:241]
	v_lshlrev_b32_e32 v240, 16, v209
	v_and_b32_e32 v241, 0xffff0000, v209
	v_pk_add_f32 v[2:3], v[2:3], v[240:241]
	s_add_u32 s42, s10, 0x20000
	s_addc_u32 s43, s11, 0
	global_load_dwordx4 v[206:209], v203, s[42:43]
	s_waitcnt vmcnt(8)
	v_pk_fma_f32 v[124:125], v[148:149], v[124:125], v[210:211]
	v_pk_fma_f32 v[126:127], v[150:151], v[126:127], v[212:213]
	s_add_u32 s98, s10, 0x0
	s_addc_u32 s99, s11, 0
	global_store_dwordx4 v203, v[124:127], s[98:99]
	s_add_u32 s42, s10, 0x20000
	s_addc_u32 s43, s11, 0
	global_load_dwordx4 v[210:213], v203, s[42:43] offset:16
	s_waitcnt vmcnt(9)
	v_pk_fma_f32 v[120:121], v[144:145], v[120:121], v[236:237]
	v_pk_fma_f32 v[122:123], v[146:147], v[122:123], v[238:239]
	s_add_u32 s98, s10, 0x0
	s_addc_u32 s99, s11, 0
	global_store_dwordx4 v203, v[120:123], s[98:99] offset:16
	s_add_u32 s42, s10, 0x20200
	s_addc_u32 s43, s11, 0
	global_load_dwordx4 v[236:239], v203, s[42:43]
	s_waitcnt vmcnt(10)
	v_pk_fma_f32 v[92:93], v[156:157], v[92:93], v[160:161]
	v_pk_fma_f32 v[94:95], v[158:159], v[94:95], v[162:163]
	s_add_u32 s98, s10, 0x200
	s_addc_u32 s99, s11, 0
	global_store_dwordx4 v203, v[92:95], s[98:99]
	s_add_u32 s42, s10, 0x20200
	s_addc_u32 s43, s11, 0
	global_load_dwordx4 v[160:163], v203, s[42:43] offset:16
	s_waitcnt vmcnt(11)
	v_pk_fma_f32 v[88:89], v[152:153], v[88:89], v[164:165]
	v_pk_fma_f32 v[90:91], v[154:155], v[90:91], v[166:167]
	s_add_u32 s98, s10, 0x200
	s_addc_u32 s99, s11, 0
	global_store_dwordx4 v203, v[88:91], s[98:99] offset:16
	s_add_u32 s42, s10, 0x30000
	s_addc_u32 s43, s11, 0
	global_load_dwordx4 v[164:167], v203, s[42:43]
	s_waitcnt vmcnt(12)
	v_pk_fma_f32 v[116:117], v[148:149], v[116:117], v[168:169]
	v_pk_fma_f32 v[118:119], v[150:151], v[118:119], v[170:171]
	s_add_u32 s98, s10, 0x10000
	s_addc_u32 s99, s11, 0
	global_store_dwordx4 v203, v[116:119], s[98:99]
	s_add_u32 s42, s10, 0x30000
	s_addc_u32 s43, s11, 0
	global_load_dwordx4 v[168:171], v203, s[42:43] offset:16
	s_waitcnt vmcnt(13)
	v_pk_fma_f32 v[112:113], v[144:145], v[112:113], v[172:173]
	v_pk_fma_f32 v[114:115], v[146:147], v[114:115], v[174:175]
	s_add_u32 s98, s10, 0x10000
	s_addc_u32 s99, s11, 0
	global_store_dwordx4 v203, v[112:115], s[98:99] offset:16
	s_add_u32 s42, s10, 0x30200
	s_addc_u32 s43, s11, 0
	global_load_dwordx4 v[172:175], v203, s[42:43]
	s_waitcnt vmcnt(14)
	v_pk_fma_f32 v[84:85], v[156:157], v[84:85], v[176:177]
	v_pk_fma_f32 v[86:87], v[158:159], v[86:87], v[178:179]
	s_add_u32 s98, s10, 0x10200
	s_addc_u32 s99, s11, 0
	global_store_dwordx4 v203, v[84:87], s[98:99]
	s_add_u32 s42, s10, 0x30200
	s_addc_u32 s43, s11, 0
	global_load_dwordx4 v[176:179], v203, s[42:43] offset:16
	s_waitcnt vmcnt(15)
	v_pk_fma_f32 v[80:81], v[152:153], v[80:81], v[180:181]
	v_pk_fma_f32 v[82:83], v[154:155], v[82:83], v[182:183]
	s_add_u32 s98, s10, 0x10200
	s_addc_u32 s99, s11, 0
	global_store_dwordx4 v203, v[80:83], s[98:99] offset:16
	s_add_u32 s42, s10, 0x80000
	s_addc_u32 s43, s11, 0
	global_load_dwordx4 v[180:183], v203, s[42:43]
	s_waitcnt vmcnt(16)
	v_pk_fma_f32 v[108:109], v[148:149], v[108:109], v[206:207]
	v_pk_fma_f32 v[110:111], v[150:151], v[110:111], v[208:209]
	s_add_u32 s98, s10, 0x20000
	s_addc_u32 s99, s11, 0
	global_store_dwordx4 v203, v[108:111], s[98:99]
	s_add_u32 s42, s10, 0x80000
	s_addc_u32 s43, s11, 0
	global_load_dwordx4 v[206:209], v203, s[42:43] offset:16
	s_waitcnt vmcnt(16)
	v_pk_fma_f32 v[104:105], v[144:145], v[104:105], v[210:211]
	v_pk_fma_f32 v[106:107], v[146:147], v[106:107], v[212:213]
	s_add_u32 s98, s10, 0x20000
	s_addc_u32 s99, s11, 0
	global_store_dwordx4 v203, v[104:107], s[98:99] offset:16
	s_add_u32 s42, s10, 0x80200
	s_addc_u32 s43, s11, 0
	global_load_dwordx4 v[210:213], v203, s[42:43]
	s_waitcnt vmcnt(16)
	v_pk_fma_f32 v[76:77], v[156:157], v[76:77], v[236:237]
	v_pk_fma_f32 v[78:79], v[158:159], v[78:79], v[238:239]
	s_add_u32 s98, s10, 0x20200
	s_addc_u32 s99, s11, 0
	global_store_dwordx4 v203, v[76:79], s[98:99]
	s_add_u32 s42, s10, 0x80200
	s_addc_u32 s43, s11, 0
	global_load_dwordx4 v[236:239], v203, s[42:43] offset:16
	s_waitcnt vmcnt(16)
	v_pk_fma_f32 v[72:73], v[152:153], v[72:73], v[160:161]
	v_pk_fma_f32 v[74:75], v[154:155], v[74:75], v[162:163]
	s_add_u32 s98, s10, 0x20200
	s_addc_u32 s99, s11, 0
	global_store_dwordx4 v203, v[72:75], s[98:99] offset:16
	s_add_u32 s42, s10, 0x90000
	s_addc_u32 s43, s11, 0
	global_load_dwordx4 v[160:163], v203, s[42:43]
	s_waitcnt vmcnt(16)
	v_pk_fma_f32 v[100:101], v[148:149], v[100:101], v[164:165]
	v_pk_fma_f32 v[102:103], v[150:151], v[102:103], v[166:167]
	s_add_u32 s98, s10, 0x30000
	s_addc_u32 s99, s11, 0
	global_store_dwordx4 v203, v[100:103], s[98:99]
	s_add_u32 s42, s10, 0x90000
	s_addc_u32 s43, s11, 0
	global_load_dwordx4 v[164:167], v203, s[42:43] offset:16
	s_waitcnt vmcnt(16)
	v_pk_fma_f32 v[96:97], v[144:145], v[96:97], v[168:169]
	v_pk_fma_f32 v[98:99], v[146:147], v[98:99], v[170:171]
	s_add_u32 s98, s10, 0x30000
	s_addc_u32 s99, s11, 0
	global_store_dwordx4 v203, v[96:99], s[98:99] offset:16
	s_add_u32 s42, s10, 0x90200
	s_addc_u32 s43, s11, 0
	global_load_dwordx4 v[168:171], v203, s[42:43]
	s_waitcnt vmcnt(16)
	v_pk_fma_f32 v[68:69], v[156:157], v[68:69], v[172:173]
	v_pk_fma_f32 v[70:71], v[158:159], v[70:71], v[174:175]
	s_add_u32 s98, s10, 0x30200
	s_addc_u32 s99, s11, 0
	global_store_dwordx4 v203, v[68:71], s[98:99]
	s_add_u32 s42, s10, 0x90200
	s_addc_u32 s43, s11, 0
	global_load_dwordx4 v[172:175], v203, s[42:43] offset:16
	s_waitcnt vmcnt(16)
	v_pk_fma_f32 v[64:65], v[152:153], v[64:65], v[176:177]
	v_pk_fma_f32 v[66:67], v[154:155], v[66:67], v[178:179]
	s_add_u32 s98, s10, 0x30200
	s_addc_u32 s99, s11, 0
	global_store_dwordx4 v203, v[64:67], s[98:99] offset:16
	s_add_u32 s42, s10, 0xa0000
	s_addc_u32 s43, s11, 0
	global_load_dwordx4 v[176:179], v203, s[42:43]
	s_waitcnt vmcnt(16)
	v_pk_fma_f32 v[60:61], v[148:149], v[60:61], v[180:181]
	v_pk_fma_f32 v[62:63], v[150:151], v[62:63], v[182:183]
	s_add_u32 s98, s10, 0x80000
	s_addc_u32 s99, s11, 0
	global_store_dwordx4 v203, v[60:63], s[98:99]
	s_add_u32 s42, s10, 0xa0000
	s_addc_u32 s43, s11, 0
	global_load_dwordx4 v[180:183], v203, s[42:43] offset:16
	s_waitcnt vmcnt(16)
	v_pk_fma_f32 v[56:57], v[144:145], v[56:57], v[206:207]
	v_pk_fma_f32 v[58:59], v[146:147], v[58:59], v[208:209]
	s_add_u32 s98, s10, 0x80000
	s_addc_u32 s99, s11, 0
	global_store_dwordx4 v203, v[56:59], s[98:99] offset:16
	s_add_u32 s42, s10, 0xa0200
	s_addc_u32 s43, s11, 0
	global_load_dwordx4 v[206:209], v203, s[42:43]
	s_waitcnt vmcnt(16)
	v_pk_fma_f32 v[28:29], v[156:157], v[28:29], v[210:211]
	v_pk_fma_f32 v[30:31], v[158:159], v[30:31], v[212:213]
	s_add_u32 s98, s10, 0x80200
	s_addc_u32 s99, s11, 0
	global_store_dwordx4 v203, v[28:31], s[98:99]
	s_add_u32 s42, s10, 0xa0200
	s_addc_u32 s43, s11, 0
	global_load_dwordx4 v[210:213], v203, s[42:43] offset:16
	s_waitcnt vmcnt(16)
	v_pk_fma_f32 v[24:25], v[152:153], v[24:25], v[236:237]
	v_pk_fma_f32 v[26:27], v[154:155], v[26:27], v[238:239]
	s_add_u32 s98, s10, 0x80200
	s_addc_u32 s99, s11, 0
	global_store_dwordx4 v203, v[24:27], s[98:99] offset:16
	s_waitcnt vmcnt(15)
	v_pk_fma_f32 v[52:53], v[148:149], v[52:53], v[160:161]
	v_pk_fma_f32 v[54:55], v[150:151], v[54:55], v[162:163]
	s_add_u32 s42, s10, 0x90000
	s_addc_u32 s43, s11, 0
	global_store_dwordx4 v203, v[52:55], s[42:43]
	s_waitcnt vmcnt(14)
	v_pk_fma_f32 v[48:49], v[144:145], v[48:49], v[164:165]
	v_pk_fma_f32 v[50:51], v[146:147], v[50:51], v[166:167]
	s_add_u32 s98, s10, 0x90000
	s_addc_u32 s99, s11, 0
	global_store_dwordx4 v203, v[48:51], s[98:99] offset:16
	s_waitcnt vmcnt(13)
	v_pk_fma_f32 v[20:21], v[156:157], v[20:21], v[168:169]
	v_pk_fma_f32 v[22:23], v[158:159], v[22:23], v[170:171]
	s_add_u32 s42, s10, 0x90200
	s_addc_u32 s43, s11, 0
	global_store_dwordx4 v203, v[20:23], s[42:43]
	s_waitcnt vmcnt(12)
	v_pk_fma_f32 v[16:17], v[152:153], v[16:17], v[172:173]
	v_pk_fma_f32 v[18:19], v[154:155], v[18:19], v[174:175]
	s_add_u32 s98, s10, 0x90200
	s_addc_u32 s99, s11, 0
	global_store_dwordx4 v203, v[16:19], s[98:99] offset:16
	s_waitcnt vmcnt(11)
	v_pk_fma_f32 v[44:45], v[148:149], v[44:45], v[176:177]
	v_pk_fma_f32 v[46:47], v[150:151], v[46:47], v[178:179]
	s_add_u32 s42, s10, 0xa0000
	s_addc_u32 s43, s11, 0
	global_store_dwordx4 v203, v[44:47], s[42:43]
	s_waitcnt vmcnt(10)
	v_pk_fma_f32 v[40:41], v[144:145], v[40:41], v[180:181]
	v_pk_fma_f32 v[42:43], v[146:147], v[42:43], v[182:183]
	s_add_u32 s98, s10, 0xa0000
	s_addc_u32 s99, s11, 0
	global_store_dwordx4 v203, v[40:43], s[98:99] offset:16
	s_waitcnt vmcnt(9)
	v_pk_fma_f32 v[12:13], v[156:157], v[12:13], v[206:207]
	v_pk_fma_f32 v[14:15], v[158:159], v[14:15], v[208:209]
	s_add_u32 s42, s10, 0xa0200
	s_addc_u32 s43, s11, 0
	global_store_dwordx4 v203, v[12:15], s[42:43]
	s_waitcnt vmcnt(8)
	v_pk_fma_f32 v[8:9], v[152:153], v[8:9], v[210:211]
	v_pk_fma_f32 v[10:11], v[154:155], v[10:11], v[212:213]
	s_add_u32 s98, s10, 0xa0200
	s_addc_u32 s99, s11, 0
	global_store_dwordx4 v203, v[8:11], s[98:99] offset:16
.Lfq_predone:
	s_mov_b32 s34, 0
	v_ashrrev_i32_e32 v205, 31, v204
	v_lshlrev_b64 v[160:161], 12, v[204:205]
	v_lshl_add_u64 v[176:177], s[10:11], 0, v[160:161]
	v_lshl_add_u64 v[178:179], v[200:201], 2, v[176:177]
	v_mov_b64_e32 v[164:165], v[120:121]
	v_mov_b64_e32 v[166:167], v[122:123]
	v_mov_b64_e32 v[160:161], v[124:125]
	v_mov_b64_e32 v[162:163], v[126:127]
	s_cmp_eq_u32 s34, 2
	v_mov_b64_e32 v[174:175], v[126:127]
	v_mov_b64_e32 v[170:171], v[122:123]
	s_cselect_b64 s[88:89], -1, 0
	s_cmp_lg_u32 s34, 2
	v_mov_b64_e32 v[172:173], v[124:125]
	v_mov_b64_e32 v[168:169], v[120:121]
	s_cbranch_scc1 .Lfq_LBB0_1428
	s_mov_b64 s[84:85], s[62:63]
	v_lshlrev_b32_e32 v180, 2, v194
	v_mov_b32_e32 v181, v185
	s_cmp_lt_i32 s30, 2
	v_lshl_add_u64 v[182:183], s[84:85], 0, v[180:181]
	flat_load_dwordx4 v[168:171], v[182:183]
	s_cbranch_scc1 .Lfq_Lskw_0
	v_add_co_u32_e32 v182, vcc, 0x20000, v182
	s_nop 1
	v_addc_co_u32_e32 v183, vcc, 0, v183, vcc
	flat_load_dwordx4 v[206:209], v[182:183]
	s_cmp_lt_i32 s30, 3
	s_cbranch_scc1 .Lfq_Lskw_0
	v_mov_b32_e32 v181, v185
	v_lshl_add_u64 v[180:181], s[84:85], 0, v[180:181]
	v_add_co_u32_e32 v180, vcc, 0x40000, v180
	s_nop 1
	v_addc_co_u32_e32 v181, vcc, 0, v181, vcc
	flat_load_dwordx4 v[180:183], v[180:181]

.Lfq_LBB0_1428:
	v_ashrrev_i32_e32 v203, 31, v202
	v_lshlrev_b64 v[206:207], 10, v[202:203]
	s_and_b64 vcc, exec, s[80:81]
	s_cbranch_vccnz .Lfq_LBB0_1430
	v_lshl_add_u64 v[172:173], v[206:207], 1, s[18:19]
	v_mul_f32_e32 v174, v140, v160
	v_mul_f32_e32 v175, v141, v161
	v_cvt_pk_bf16_f32 v168, v174, v175
	v_mul_f32_e32 v178, v142, v162
	v_mul_f32_e32 v179, v143, v163
	v_cvt_pk_bf16_f32 v169, v178, v179
	v_lshl_add_u64 v[172:173], v[200:201], 1, v[172:173]
	v_mul_f32_e32 v180, v136, v164
	v_mul_f32_e32 v181, v137, v165
	v_cvt_pk_bf16_f32 v170, v180, v181
	v_mul_f32_e32 v182, v138, v166
	v_mul_f32_e32 v183, v139, v167
	v_cvt_pk_bf16_f32 v171, v182, v183
	global_store_dwordx4 v[172:173], v[168:171], off
	s_nop 1
	v_mov_b32_e32 v168, v185
	v_mov_b32_e32 v169, v185
	v_cvt_pk_fp8_f32 v168, v174, v175
	v_cvt_pk_fp8_f32 v169, v180, v181
	v_lshl_add_u64 v[170:171], s[70:71], 0, v[206:207]
	v_lshl_add_u64 v[170:171], v[170:171], 0, v[200:201]
	v_cvt_pk_fp8_f32 v168, v178, v179 op_sel:[0,0,1]
	v_cvt_pk_fp8_f32 v169, v182, v183 op_sel:[0,0,1]
	global_store_dwordx2 v[170:171], v[168:169], off
.Lfq_LBB0_1430:
	v_lshl_add_u64 v[208:209], v[200:201], 2, v[176:177]
	v_mov_b64_e32 v[168:169], v[88:89]
	v_mov_b64_e32 v[170:171], v[90:91]
	v_mov_b64_e32 v[172:173], v[92:93]
	v_mov_b64_e32 v[174:175], v[94:95]
	v_cndmask_b32_e64 v176, 0, 1, s[88:89]
	v_cmp_ne_u32_e64 s[84:85], 1, v176
	v_mov_b64_e32 v[182:183], v[94:95]
	v_mov_b64_e32 v[178:179], v[90:91]
	s_andn2_b64 vcc, exec, s[88:89]
	v_mov_b64_e32 v[180:181], v[92:93]
	v_mov_b64_e32 v[176:177], v[88:89]
	s_cbranch_vccnz .Lfq_LBB0_1435
	v_readlane_b32 s88, v242, 16
	v_readlane_b32 s89, v242, 17
	v_lshlrev_b32_e32 v210, 2, v194
	v_mov_b32_e32 v211, v185
	s_cmp_lt_i32 s30, 2
	v_lshl_add_u64 v[212:213], s[88:89], 0, v[210:211]
	flat_load_dwordx4 v[176:179], v[212:213]
	s_cbranch_scc1 .Lfq_Lskw_1
	v_add_co_u32_e32 v212, vcc, 0x20000, v212
	s_nop 1
	v_addc_co_u32_e32 v213, vcc, 0, v213, vcc
	flat_load_dwordx4 v[236:239], v[212:213]
	s_cmp_lt_i32 s30, 3
	s_cbranch_scc1 .Lfq_Lskw_1
	v_mov_b32_e32 v211, v185
	v_lshl_add_u64 v[210:211], s[88:89], 0, v[210:211]
	v_add_co_u32_e32 v210, vcc, 0x40000, v210
	s_nop 1
	v_addc_co_u32_e32 v211, vcc, 0, v211, vcc
	flat_load_dwordx4 v[210:213], v[210:211]

.Lfq_LBB0_1435:
	s_and_b64 vcc, exec, s[80:81]
	s_cbranch_vccnz .Lfq_LBB0_1437
	v_lshl_add_u64 v[180:181], v[206:207], 1, s[18:19]
	v_mul_f32_e32 v182, v132, v172
	v_mul_f32_e32 v183, v133, v173
	v_cvt_pk_bf16_f32 v176, v182, v183
	v_mul_f32_e32 v203, v134, v174
	v_mul_f32_e32 v205, v135, v175
	v_cvt_pk_bf16_f32 v177, v203, v205
	v_lshl_add_u64 v[180:181], v[200:201], 1, v[180:181]
	v_mul_f32_e32 v208, v128, v168
	v_mul_f32_e32 v209, v129, v169
	v_cvt_pk_bf16_f32 v178, v208, v209
	v_mul_f32_e32 v210, v130, v170
	v_mul_f32_e32 v211, v131, v171
	v_cvt_pk_bf16_f32 v179, v210, v211
	global_store_dwordx4 v[180:181], v[176:179], off offset:256
	s_nop 1
	v_mov_b32_e32 v176, v185
	v_mov_b32_e32 v177, v185
	v_cvt_pk_fp8_f32 v176, v182, v183
	v_cvt_pk_fp8_f32 v177, v208, v209
	v_lshl_add_u64 v[178:179], s[70:71], 0, v[206:207]
	v_lshl_add_u64 v[178:179], v[178:179], 0, v[200:201]
	v_cvt_pk_fp8_f32 v176, v203, v205 op_sel:[0,0,1]
	v_cvt_pk_fp8_f32 v177, v210, v211 op_sel:[0,0,1]
	global_store_dwordx2 v[178:179], v[176:177], off offset:128

.Lfq_LBB0_1442:
	v_ashrrev_i32_e32 v205, 31, v204
	v_lshlrev_b64 v[160:161], 12, v[204:205]
	v_lshl_add_u64 v[176:177], s[10:11], 0, v[160:161]
	v_lshl_add_u64 v[178:179], v[200:201], 2, v[176:177]
	v_mov_b64_e32 v[164:165], v[112:113]
	v_mov_b64_e32 v[166:167], v[114:115]
	v_mov_b64_e32 v[160:161], v[116:117]
	v_mov_b64_e32 v[162:163], v[118:119]
	v_mov_b64_e32 v[174:175], v[118:119]
	v_mov_b64_e32 v[170:171], v[114:115]
	s_and_b64 vcc, exec, s[84:85]
	v_mov_b64_e32 v[172:173], v[116:117]
	v_mov_b64_e32 v[168:169], v[112:113]
	s_cbranch_vccnz .Lfq_LBB0_1447
	v_readlane_b32 s88, v242, 18
	v_readlane_b32 s89, v242, 19
	v_lshlrev_b32_e32 v180, 2, v194
	v_mov_b32_e32 v181, v185
	s_cmp_lt_i32 s30, 2
	v_lshl_add_u64 v[182:183], s[88:89], 0, v[180:181]
	flat_load_dwordx4 v[168:171], v[182:183]
	s_cbranch_scc1 .Lfq_Lskw_2
	v_add_co_u32_e32 v182, vcc, 0x20000, v182
	s_nop 1
	v_addc_co_u32_e32 v183, vcc, 0, v183, vcc
	flat_load_dwordx4 v[206:209], v[182:183]
	s_cmp_lt_i32 s30, 3
	s_cbranch_scc1 .Lfq_Lskw_2
	v_mov_b32_e32 v181, v185
	v_lshl_add_u64 v[180:181], s[88:89], 0, v[180:181]
	v_add_co_u32_e32 v180, vcc, 0x40000, v180
	s_nop 1
	v_addc_co_u32_e32 v181, vcc, 0, v181, vcc
	flat_load_dwordx4 v[180:183], v[180:181]

.Lfq_LBB0_1449:
	v_lshl_add_u64 v[208:209], v[200:201], 2, v[176:177]
	v_mov_b64_e32 v[168:169], v[80:81]
	v_mov_b64_e32 v[170:171], v[82:83]
	v_mov_b64_e32 v[172:173], v[84:85]
	v_mov_b64_e32 v[174:175], v[86:87]
	v_mov_b64_e32 v[182:183], v[86:87]
	v_mov_b64_e32 v[178:179], v[82:83]
	s_and_b64 vcc, exec, s[84:85]
	v_mov_b64_e32 v[180:181], v[84:85]
	v_mov_b64_e32 v[176:177], v[80:81]
	s_cbranch_vccnz .Lfq_LBB0_1454
	v_readlane_b32 s88, v242, 20
	v_readlane_b32 s89, v242, 21
	v_lshlrev_b32_e32 v210, 2, v194
	v_mov_b32_e32 v211, v185
	s_cmp_lt_i32 s30, 2
	v_lshl_add_u64 v[212:213], s[88:89], 0, v[210:211]
	flat_load_dwordx4 v[176:179], v[212:213]
	s_cbranch_scc1 .Lfq_Lskw_3
	v_add_co_u32_e32 v212, vcc, 0x20000, v212
	s_nop 1
	v_addc_co_u32_e32 v213, vcc, 0, v213, vcc
	flat_load_dwordx4 v[238:241], v[212:213]
	s_cmp_lt_i32 s30, 3
	s_cbranch_scc1 .Lfq_Lskw_3
	v_mov_b32_e32 v211, v185
	v_lshl_add_u64 v[210:211], s[88:89], 0, v[210:211]
	v_add_co_u32_e32 v210, vcc, 0x40000, v210
	s_nop 1
	v_addc_co_u32_e32 v211, vcc, 0, v211, vcc
	flat_load_dwordx4 v[210:213], v[210:211]

.Lfq_LBB0_1461:
	v_ashrrev_i32_e32 v205, 31, v204
	v_lshlrev_b64 v[160:161], 12, v[204:205]
	v_lshl_add_u64 v[176:177], s[10:11], 0, v[160:161]
	v_lshl_add_u64 v[178:179], v[200:201], 2, v[176:177]
	v_mov_b64_e32 v[164:165], v[104:105]
	v_mov_b64_e32 v[166:167], v[106:107]
	v_mov_b64_e32 v[160:161], v[108:109]
	v_mov_b64_e32 v[162:163], v[110:111]
	v_mov_b64_e32 v[174:175], v[110:111]
	v_mov_b64_e32 v[170:171], v[106:107]
	s_and_b64 vcc, exec, s[84:85]
	v_mov_b64_e32 v[172:173], v[108:109]
	v_mov_b64_e32 v[168:169], v[104:105]
	s_cbranch_vccnz .Lfq_LBB0_1466
	v_readlane_b32 s88, v242, 22
	v_readlane_b32 s89, v242, 23
	v_lshlrev_b32_e32 v180, 2, v194
	v_mov_b32_e32 v181, v185
	s_cmp_lt_i32 s30, 2
	v_lshl_add_u64 v[182:183], s[88:89], 0, v[180:181]
	flat_load_dwordx4 v[168:171], v[182:183]
	s_cbranch_scc1 .Lfq_Lskw_4
	v_add_co_u32_e32 v182, vcc, 0x20000, v182
	s_nop 1
	v_addc_co_u32_e32 v183, vcc, 0, v183, vcc
	flat_load_dwordx4 v[206:209], v[182:183]
	s_cmp_lt_i32 s30, 3
	s_cbranch_scc1 .Lfq_Lskw_4
	v_mov_b32_e32 v181, v185
	v_lshl_add_u64 v[180:181], s[88:89], 0, v[180:181]
	v_add_co_u32_e32 v180, vcc, 0x40000, v180
	s_nop 1
	v_addc_co_u32_e32 v181, vcc, 0, v181, vcc
	flat_load_dwordx4 v[180:183], v[180:181]

.Lfq_LBB0_1468:
	v_lshl_add_u64 v[208:209], v[200:201], 2, v[176:177]
	v_mov_b64_e32 v[168:169], v[72:73]
	v_mov_b64_e32 v[170:171], v[74:75]
	v_mov_b64_e32 v[172:173], v[76:77]
	v_mov_b64_e32 v[174:175], v[78:79]
	v_mov_b64_e32 v[182:183], v[78:79]
	v_mov_b64_e32 v[178:179], v[74:75]
	s_and_b64 vcc, exec, s[84:85]
	v_mov_b64_e32 v[180:181], v[76:77]
	v_mov_b64_e32 v[176:177], v[72:73]
	s_cbranch_vccnz .Lfq_LBB0_1473
	v_readlane_b32 s88, v242, 24
	v_readlane_b32 s89, v242, 25
	v_lshlrev_b32_e32 v210, 2, v194
	v_mov_b32_e32 v211, v185
	s_cmp_lt_i32 s30, 2
	v_lshl_add_u64 v[212:213], s[88:89], 0, v[210:211]
	flat_load_dwordx4 v[176:179], v[212:213]
	s_cbranch_scc1 .Lfq_Lskw_5
	v_add_co_u32_e32 v212, vcc, 0x20000, v212
	s_nop 1
	v_addc_co_u32_e32 v213, vcc, 0, v213, vcc
	flat_load_dwordx4 v[238:241], v[212:213]
	s_cmp_lt_i32 s30, 3
	s_cbranch_scc1 .Lfq_Lskw_5
	v_mov_b32_e32 v211, v185
	v_lshl_add_u64 v[210:211], s[88:89], 0, v[210:211]
	v_add_co_u32_e32 v210, vcc, 0x40000, v210
	s_nop 1
	v_addc_co_u32_e32 v211, vcc, 0, v211, vcc
	flat_load_dwordx4 v[210:213], v[210:211]

.Lfq_LBB0_1480:
	v_ashrrev_i32_e32 v205, 31, v204
	v_lshlrev_b64 v[160:161], 12, v[204:205]
	v_lshl_add_u64 v[176:177], s[10:11], 0, v[160:161]
	v_lshl_add_u64 v[178:179], v[200:201], 2, v[176:177]
	v_mov_b64_e32 v[164:165], v[96:97]
	v_mov_b64_e32 v[166:167], v[98:99]
	v_mov_b64_e32 v[160:161], v[100:101]
	v_mov_b64_e32 v[162:163], v[102:103]
	v_mov_b64_e32 v[174:175], v[102:103]
	v_mov_b64_e32 v[170:171], v[98:99]
	s_and_b64 vcc, exec, s[84:85]
	v_mov_b64_e32 v[172:173], v[100:101]
	v_mov_b64_e32 v[168:169], v[96:97]
	s_cbranch_vccnz .Lfq_LBB0_1485
	v_readlane_b32 s88, v242, 26
	v_readlane_b32 s89, v242, 27
	v_lshlrev_b32_e32 v180, 2, v194
	v_mov_b32_e32 v181, v185
	s_cmp_lt_i32 s30, 2
	v_lshl_add_u64 v[182:183], s[88:89], 0, v[180:181]
	flat_load_dwordx4 v[168:171], v[182:183]
	s_cbranch_scc1 .Lfq_Lskw_6
	v_add_co_u32_e32 v182, vcc, 0x20000, v182
	s_nop 1
	v_addc_co_u32_e32 v183, vcc, 0, v183, vcc
	flat_load_dwordx4 v[206:209], v[182:183]
	s_cmp_lt_i32 s30, 3
	s_cbranch_scc1 .Lfq_Lskw_6
	v_mov_b32_e32 v181, v185
	v_lshl_add_u64 v[180:181], s[88:89], 0, v[180:181]
	v_add_co_u32_e32 v180, vcc, 0x40000, v180
	s_nop 1
	v_addc_co_u32_e32 v181, vcc, 0, v181, vcc
	flat_load_dwordx4 v[180:183], v[180:181]

.Lfq_LBB0_1487:
	v_lshl_add_u64 v[208:209], v[200:201], 2, v[176:177]
	v_mov_b64_e32 v[168:169], v[64:65]
	v_mov_b64_e32 v[170:171], v[66:67]
	v_mov_b64_e32 v[172:173], v[68:69]
	v_mov_b64_e32 v[174:175], v[70:71]
	v_mov_b64_e32 v[182:183], v[70:71]
	v_mov_b64_e32 v[178:179], v[66:67]
	s_and_b64 vcc, exec, s[84:85]
	v_mov_b64_e32 v[180:181], v[68:69]
	v_mov_b64_e32 v[176:177], v[64:65]
	s_cbranch_vccnz .Lfq_LBB0_1492
	v_readlane_b32 s88, v242, 28
	v_readlane_b32 s89, v242, 29
	v_lshlrev_b32_e32 v210, 2, v194
	v_mov_b32_e32 v211, v185
	s_cmp_lt_i32 s30, 2
	v_lshl_add_u64 v[212:213], s[88:89], 0, v[210:211]
	flat_load_dwordx4 v[176:179], v[212:213]
	s_cbranch_scc1 .Lfq_Lskw_7
	v_add_co_u32_e32 v212, vcc, 0x20000, v212
	s_nop 1
	v_addc_co_u32_e32 v213, vcc, 0, v213, vcc
	flat_load_dwordx4 v[238:241], v[212:213]
	s_cmp_lt_i32 s30, 3
	s_cbranch_scc1 .Lfq_Lskw_7
	v_mov_b32_e32 v211, v185
	v_lshl_add_u64 v[210:211], s[88:89], 0, v[210:211]
	v_add_co_u32_e32 v210, vcc, 0x40000, v210
	s_nop 1
	v_addc_co_u32_e32 v211, vcc, 0, v211, vcc
	flat_load_dwordx4 v[210:213], v[210:211]

.Lfq_LBB0_1499:
	v_ashrrev_i32_e32 v205, 31, v204
	v_lshlrev_b64 v[160:161], 12, v[204:205]
	v_lshl_add_u64 v[176:177], s[10:11], 0, v[160:161]
	v_lshl_add_u64 v[178:179], v[200:201], 2, v[176:177]
	v_mov_b64_e32 v[164:165], v[56:57]
	v_mov_b64_e32 v[166:167], v[58:59]
	v_mov_b64_e32 v[160:161], v[60:61]
	v_mov_b64_e32 v[162:163], v[62:63]
	v_mov_b64_e32 v[174:175], v[62:63]
	v_mov_b64_e32 v[170:171], v[58:59]
	s_and_b64 vcc, exec, s[84:85]
	v_mov_b64_e32 v[172:173], v[60:61]
	v_mov_b64_e32 v[168:169], v[56:57]
	s_cbranch_vccnz .Lfq_LBB0_1504
	v_readlane_b32 s88, v242, 30
	v_readlane_b32 s89, v242, 31
	v_lshlrev_b32_e32 v180, 2, v194
	v_mov_b32_e32 v181, v185
	s_cmp_lt_i32 s30, 2
	v_lshl_add_u64 v[182:183], s[88:89], 0, v[180:181]
	flat_load_dwordx4 v[168:171], v[182:183]
	s_cbranch_scc1 .Lfq_Lskw_8
	v_add_co_u32_e32 v182, vcc, 0x20000, v182
	s_nop 1
	v_addc_co_u32_e32 v183, vcc, 0, v183, vcc
	flat_load_dwordx4 v[206:209], v[182:183]
	s_cmp_lt_i32 s30, 3
	s_cbranch_scc1 .Lfq_Lskw_8
	v_mov_b32_e32 v181, v185
	v_lshl_add_u64 v[180:181], s[88:89], 0, v[180:181]
	v_add_co_u32_e32 v180, vcc, 0x40000, v180
	s_nop 1
	v_addc_co_u32_e32 v181, vcc, 0, v181, vcc
	flat_load_dwordx4 v[180:183], v[180:181]

.Lfq_LBB0_1506:
	v_lshl_add_u64 v[208:209], v[200:201], 2, v[176:177]
	v_mov_b64_e32 v[168:169], v[24:25]
	v_mov_b64_e32 v[170:171], v[26:27]
	v_mov_b64_e32 v[172:173], v[28:29]
	v_mov_b64_e32 v[174:175], v[30:31]
	v_mov_b64_e32 v[182:183], v[30:31]
	v_mov_b64_e32 v[178:179], v[26:27]
	s_and_b64 vcc, exec, s[84:85]
	v_mov_b64_e32 v[180:181], v[28:29]
	v_mov_b64_e32 v[176:177], v[24:25]
	s_cbranch_vccnz .Lfq_LBB0_1511
	v_readlane_b32 s88, v242, 32
	v_readlane_b32 s89, v242, 33
	v_lshlrev_b32_e32 v210, 2, v194
	v_mov_b32_e32 v211, v185
	s_cmp_lt_i32 s30, 2
	v_lshl_add_u64 v[212:213], s[88:89], 0, v[210:211]
	flat_load_dwordx4 v[176:179], v[212:213]
	s_cbranch_scc1 .Lfq_Lskw_9
	v_add_co_u32_e32 v212, vcc, 0x20000, v212
	s_nop 1
	v_addc_co_u32_e32 v213, vcc, 0, v213, vcc
	flat_load_dwordx4 v[238:241], v[212:213]
	s_cmp_lt_i32 s30, 3
	s_cbranch_scc1 .Lfq_Lskw_9
	v_mov_b32_e32 v211, v185
	v_lshl_add_u64 v[210:211], s[88:89], 0, v[210:211]
	v_add_co_u32_e32 v210, vcc, 0x40000, v210
	s_nop 1
	v_addc_co_u32_e32 v211, vcc, 0, v211, vcc
	flat_load_dwordx4 v[210:213], v[210:211]

.Lfq_LBB0_1518:
	v_ashrrev_i32_e32 v205, 31, v204
	v_lshlrev_b64 v[160:161], 12, v[204:205]
	v_lshl_add_u64 v[176:177], s[10:11], 0, v[160:161]
	v_lshl_add_u64 v[178:179], v[200:201], 2, v[176:177]
	v_mov_b64_e32 v[164:165], v[48:49]
	v_mov_b64_e32 v[166:167], v[50:51]
	v_mov_b64_e32 v[160:161], v[52:53]
	v_mov_b64_e32 v[162:163], v[54:55]
	v_mov_b64_e32 v[174:175], v[54:55]
	v_mov_b64_e32 v[170:171], v[50:51]
	s_and_b64 vcc, exec, s[84:85]
	v_mov_b64_e32 v[172:173], v[52:53]
	v_mov_b64_e32 v[168:169], v[48:49]
	s_cbranch_vccnz .Lfq_LBB0_1523
	v_readlane_b32 s88, v242, 34
	v_readlane_b32 s89, v242, 35
	v_lshlrev_b32_e32 v180, 2, v194
	v_mov_b32_e32 v181, v185
	s_cmp_lt_i32 s30, 2
	v_lshl_add_u64 v[182:183], s[88:89], 0, v[180:181]
	flat_load_dwordx4 v[168:171], v[182:183]
	s_cbranch_scc1 .Lfq_Lskw_10
	v_add_co_u32_e32 v182, vcc, 0x20000, v182
	s_nop 1
	v_addc_co_u32_e32 v183, vcc, 0, v183, vcc
	flat_load_dwordx4 v[206:209], v[182:183]
	s_cmp_lt_i32 s30, 3
	s_cbranch_scc1 .Lfq_Lskw_10
	v_mov_b32_e32 v181, v185
	v_lshl_add_u64 v[180:181], s[88:89], 0, v[180:181]
	v_add_co_u32_e32 v180, vcc, 0x40000, v180
	s_nop 1
	v_addc_co_u32_e32 v181, vcc, 0, v181, vcc
	flat_load_dwordx4 v[180:183], v[180:181]

.Lfq_LBB0_1525:
	v_lshl_add_u64 v[208:209], v[200:201], 2, v[176:177]
	v_mov_b64_e32 v[168:169], v[16:17]
	v_mov_b64_e32 v[170:171], v[18:19]
	v_mov_b64_e32 v[172:173], v[20:21]
	v_mov_b64_e32 v[174:175], v[22:23]
	v_mov_b64_e32 v[182:183], v[22:23]
	v_mov_b64_e32 v[178:179], v[18:19]
	s_and_b64 vcc, exec, s[84:85]
	v_mov_b64_e32 v[180:181], v[20:21]
	v_mov_b64_e32 v[176:177], v[16:17]
	s_cbranch_vccnz .Lfq_LBB0_1530
	v_readlane_b32 s88, v242, 36
	v_readlane_b32 s89, v242, 37
	v_lshlrev_b32_e32 v210, 2, v194
	v_mov_b32_e32 v211, v185
	s_cmp_lt_i32 s30, 2
	v_lshl_add_u64 v[212:213], s[88:89], 0, v[210:211]
	flat_load_dwordx4 v[176:179], v[212:213]
	s_cbranch_scc1 .Lfq_Lskw_11
	v_add_co_u32_e32 v212, vcc, 0x20000, v212
	s_nop 1
	v_addc_co_u32_e32 v213, vcc, 0, v213, vcc
	flat_load_dwordx4 v[238:241], v[212:213]
	s_cmp_lt_i32 s30, 3
	s_cbranch_scc1 .Lfq_Lskw_11
	v_mov_b32_e32 v211, v185
	v_lshl_add_u64 v[210:211], s[88:89], 0, v[210:211]
	v_add_co_u32_e32 v210, vcc, 0x40000, v210
	s_nop 1
	v_addc_co_u32_e32 v211, vcc, 0, v211, vcc
	flat_load_dwordx4 v[210:213], v[210:211]

.Lfq_LBB0_1537:
	v_ashrrev_i32_e32 v205, 31, v204
	v_lshlrev_b64 v[160:161], 12, v[204:205]
	v_lshl_add_u64 v[176:177], s[10:11], 0, v[160:161]
	v_lshl_add_u64 v[178:179], v[200:201], 2, v[176:177]
	v_mov_b64_e32 v[164:165], v[40:41]
	v_mov_b64_e32 v[166:167], v[42:43]
	v_mov_b64_e32 v[160:161], v[44:45]
	v_mov_b64_e32 v[162:163], v[46:47]
	v_mov_b64_e32 v[174:175], v[46:47]
	v_mov_b64_e32 v[170:171], v[42:43]
	s_and_b64 vcc, exec, s[84:85]
	v_mov_b64_e32 v[172:173], v[44:45]
	v_mov_b64_e32 v[168:169], v[40:41]
	s_cbranch_vccnz .Lfq_LBB0_1542
	v_readlane_b32 s88, v242, 38
	v_readlane_b32 s89, v242, 39
	v_lshlrev_b32_e32 v180, 2, v194
	v_mov_b32_e32 v181, v185
	s_cmp_lt_i32 s30, 2
	v_lshl_add_u64 v[182:183], s[88:89], 0, v[180:181]
	flat_load_dwordx4 v[168:171], v[182:183]
	s_cbranch_scc1 .Lfq_Lskw_12
	v_add_co_u32_e32 v182, vcc, 0x20000, v182
	s_nop 1
	v_addc_co_u32_e32 v183, vcc, 0, v183, vcc
	flat_load_dwordx4 v[206:209], v[182:183]
	s_cmp_lt_i32 s30, 3
	s_cbranch_scc1 .Lfq_Lskw_12
	v_mov_b32_e32 v181, v185
	v_lshl_add_u64 v[180:181], s[88:89], 0, v[180:181]
	v_add_co_u32_e32 v180, vcc, 0x40000, v180
	s_nop 1
	v_addc_co_u32_e32 v181, vcc, 0, v181, vcc
	flat_load_dwordx4 v[180:183], v[180:181]

.Lfq_LBB0_1544:
	v_lshl_add_u64 v[208:209], v[200:201], 2, v[176:177]
	v_mov_b64_e32 v[168:169], v[8:9]
	v_mov_b64_e32 v[170:171], v[10:11]
	v_mov_b64_e32 v[172:173], v[12:13]
	v_mov_b64_e32 v[174:175], v[14:15]
	v_mov_b64_e32 v[182:183], v[14:15]
	v_mov_b64_e32 v[178:179], v[10:11]
	s_and_b64 vcc, exec, s[84:85]
	v_mov_b64_e32 v[180:181], v[12:13]
	v_mov_b64_e32 v[176:177], v[8:9]
	s_cbranch_vccnz .Lfq_LBB0_1549
	v_readlane_b32 s88, v242, 40
	v_readlane_b32 s89, v242, 41
	v_lshlrev_b32_e32 v210, 2, v194
	v_mov_b32_e32 v211, v185
	s_cmp_lt_i32 s30, 2
	v_lshl_add_u64 v[212:213], s[88:89], 0, v[210:211]
	flat_load_dwordx4 v[176:179], v[212:213]
	s_cbranch_scc1 .Lfq_Lskw_13
	v_add_co_u32_e32 v212, vcc, 0x20000, v212
	s_nop 1
	v_addc_co_u32_e32 v213, vcc, 0, v213, vcc
	flat_load_dwordx4 v[238:241], v[212:213]
	s_cmp_lt_i32 s30, 3
	s_cbranch_scc1 .Lfq_Lskw_13
	v_mov_b32_e32 v211, v185
	v_lshl_add_u64 v[210:211], s[88:89], 0, v[210:211]
	v_add_co_u32_e32 v210, vcc, 0x40000, v210
	s_nop 1
	v_addc_co_u32_e32 v211, vcc, 0, v211, vcc
	flat_load_dwordx4 v[210:213], v[210:211]
